# conversion work split: idle workgroups 15 of 16 steps, busy workgroups take the last w_up step after their fifth unit
# baseline (speedup 1.0000x reference)
.LBB0_332:
	s_abs_i32 s0, s33
	s_waitcnt vmcnt(34)
	v_cvt_f32_u32_e32 v1, s0
	s_sub_i32 s1, 0, s0
	v_rcp_iflag_f32_e32 v1, v1
	s_nop 0
	v_mul_f32_e32 v1, 0x4f7ffffe, v1
	v_cvt_u32_f32_e32 v1, v1
	s_nop 0
	v_readfirstlane_b32 s3, v1
	s_mul_i32 s1, s1, s3
	s_mul_hi_u32 s1, s3, s1
	s_add_i32 s3, s3, s1
	s_mul_hi_u32 s1, s3, 0x480
	s_mul_i32 s1, s1, s0
	s_sub_i32 s1, 0x480, s1
	s_sub_i32 s3, s1, s0
	s_cmp_ge_u32 s1, s0
	s_cselect_b32 s1, s3, s1
	s_sub_i32 s3, s1, s0
	s_cmp_ge_u32 s1, s0
	s_cselect_b32 s10, s3, s1
	v_readlane_b32 s0, v254, 2
	s_sub_i32 s0, s0, s10
	s_cmp_lt_i32 s0, 0
	s_cbranch_scc1 .Lconv_classA
	s_lshl_b32 s0, s0, 3
	s_add_i32 s0, s0, s78
	v_readlane_b32 s70, v254, 0
	v_readlane_b32 s71, v254, 1
	s_sub_u32 s70, s70, 0xc8
	s_subb_u32 s71, s71, 0
	s_load_dwordx4 s[4:7], s[70:71], 0x68
	s_load_dwordx2 s[8:9], s[70:71], 0x78
	s_load_dwordx2 s[10:11], s[70:71], 0x90
	s_add_u32 s12, s26, 0x2600000
	s_addc_u32 s13, s27, 0
	s_add_u32 s30, s26, 0x3200000
	s_addc_u32 s31, s27, 0
	s_add_u32 s42, s26, 0x3a00000
	s_addc_u32 s43, s27, 0
	v_and_b32_e32 v7, 63, v0
	v_lshrrev_b32_e32 v8, 3, v7
	v_and_b32_e32 v9, 7, v7
	v_lshlrev_b32_e32 v1, 13, v8
	v_lshl_add_u32 v1, v9, 4, v1
	v_mul_u32_u24_e32 v2, 0xb000, v8
	v_lshl_add_u32 v2, v9, 4, v2
	s_lshl_b32 s1, s78, 14
	v_mul_u32_u24_e32 v3, 33, v8
	v_lshl_add_u32 v3, v9, 2, v3
	v_lshl_add_u32 v3, v3, 2, s1
	v_mul_u32_u24_e32 v4, 0x108, v9
	v_add_u32_e32 v4, v4, v8
	v_lshl_add_u32 v4, v4, 2, s1
	v_mul_u32_u24_e32 v5, 0x1800, v8
	v_lshl_add_u32 v5, v9, 4, v5
	v_lshlrev_b32_e32 v6, 12, v8
	v_lshl_add_u32 v6, v9, 4, v6
	s_waitcnt lgkmcnt(0)
	s_mov_b32 s3, s0
	s_lshr_b32 s29, s3, 6
	s_and_b32 s35, s3, 63
	s_lshl_b32 s58, s29, 19
	s_lshl_b32 s59, s35, 7
	s_add_u32 s58, s58, s59
	s_add_u32 s46, s4, s58
	s_addc_u32 s47, s5, 0
	global_load_dwordx4 v[16:19], v1, s[46:47] nt
	v_add_u32_e32 v7, 0x10000, v1
	global_load_dwordx4 v[20:23], v7, s[46:47] nt
	v_add_u32_e32 v7, 0x20000, v1
	global_load_dwordx4 v[24:27], v7, s[46:47] nt
	v_add_u32_e32 v7, 0x30000, v1
	global_load_dwordx4 v[28:31], v7, s[46:47] nt
	v_add_u32_e32 v7, 0x40000, v1
	global_load_dwordx4 v[32:35], v7, s[46:47] nt
	v_add_u32_e32 v7, 0x50000, v1
	global_load_dwordx4 v[36:39], v7, s[46:47] nt
	v_add_u32_e32 v7, 0x60000, v1
	global_load_dwordx4 v[40:43], v7, s[46:47] nt
	v_add_u32_e32 v7, 0x70000, v1
	global_load_dwordx4 v[44:47], v7, s[46:47] nt
	s_add_i32 s3, s0, 1024
	s_lshr_b32 s29, s3, 6
	s_and_b32 s35, s3, 63
	s_lshl_b32 s58, s29, 19
	s_lshl_b32 s59, s35, 7
	s_add_u32 s58, s58, s59
	s_add_u32 s46, s4, s58
	s_addc_u32 s47, s5, 0
	global_load_dwordx4 v[48:51], v1, s[46:47] nt
	v_add_u32_e32 v7, 0x10000, v1
	global_load_dwordx4 v[52:55], v7, s[46:47] nt
	v_add_u32_e32 v7, 0x20000, v1
	global_load_dwordx4 v[56:59], v7, s[46:47] nt
	v_add_u32_e32 v7, 0x30000, v1
	global_load_dwordx4 v[60:63], v7, s[46:47] nt
	v_add_u32_e32 v7, 0x40000, v1
	global_load_dwordx4 v[64:67], v7, s[46:47] nt
	v_add_u32_e32 v7, 0x50000, v1
	global_load_dwordx4 v[68:71], v7, s[46:47] nt
	v_add_u32_e32 v7, 0x60000, v1
	global_load_dwordx4 v[72:75], v7, s[46:47] nt
	v_add_u32_e32 v7, 0x70000, v1
	global_load_dwordx4 v[76:79], v7, s[46:47] nt
	s_mov_b32 s3, s0
	s_lshr_b32 s29, s3, 6
	s_and_b32 s35, s3, 63
	s_lshl_b32 s58, s29, 19
	s_lshl_b32 s59, s35, 7
	s_add_u32 s58, s58, s59
	s_add_u32 s46, s6, s58
	s_addc_u32 s47, s7, 0
	global_load_dwordx4 v[80:83], v1, s[46:47] nt
	v_add_u32_e32 v7, 0x10000, v1
	global_load_dwordx4 v[84:87], v7, s[46:47] nt
	v_add_u32_e32 v7, 0x20000, v1
	global_load_dwordx4 v[88:91], v7, s[46:47] nt
	v_add_u32_e32 v7, 0x30000, v1
	global_load_dwordx4 v[92:95], v7, s[46:47] nt
	v_add_u32_e32 v7, 0x40000, v1
	global_load_dwordx4 v[96:99], v7, s[46:47] nt
	v_add_u32_e32 v7, 0x50000, v1
	global_load_dwordx4 v[100:103], v7, s[46:47] nt
	v_add_u32_e32 v7, 0x60000, v1
	global_load_dwordx4 v[104:107], v7, s[46:47] nt
	v_add_u32_e32 v7, 0x70000, v1
	global_load_dwordx4 v[108:111], v7, s[46:47] nt
	s_waitcnt vmcnt(16)
	ds_write_b32 v3, v16
	ds_write_b32 v3, v17 offset:4
	ds_write_b32 v3, v18 offset:8
	ds_write_b32 v3, v19 offset:12
	ds_write_b32 v3, v20 offset:1056
	ds_write_b32 v3, v21 offset:1060
	ds_write_b32 v3, v22 offset:1064
	ds_write_b32 v3, v23 offset:1068
	ds_write_b32 v3, v24 offset:2112
	ds_write_b32 v3, v25 offset:2116
	ds_write_b32 v3, v26 offset:2120
	ds_write_b32 v3, v27 offset:2124
	ds_write_b32 v3, v28 offset:3168
	ds_write_b32 v3, v29 offset:3172
	ds_write_b32 v3, v30 offset:3176
	ds_write_b32 v3, v31 offset:3180
	ds_write_b32 v3, v32 offset:4224
	ds_write_b32 v3, v33 offset:4228
	ds_write_b32 v3, v34 offset:4232
	ds_write_b32 v3, v35 offset:4236
	ds_write_b32 v3, v36 offset:5280
	ds_write_b32 v3, v37 offset:5284
	ds_write_b32 v3, v38 offset:5288
	ds_write_b32 v3, v39 offset:5292
	ds_write_b32 v3, v40 offset:6336
	ds_write_b32 v3, v41 offset:6340
	ds_write_b32 v3, v42 offset:6344
	ds_write_b32 v3, v43 offset:6348
	ds_write_b32 v3, v44 offset:7392
	ds_write_b32 v3, v45 offset:7396
	ds_write_b32 v3, v46 offset:7400
	ds_write_b32 v3, v47 offset:7404
	s_waitcnt lgkmcnt(0)
	s_mov_b32 s3, s0
	s_lshr_b32 s29, s3, 6
	s_and_b32 s35, s3, 63
	s_mul_i32 s58, s35, 0x30000
	s_lshl_b32 s59, s29, 7
	s_add_u32 s58, s58, s59
	s_add_u32 s48, s12, s58
	s_addc_u32 s49, s13, 0
	ds_read2_b32 v[8:9], v4 offset0:0 offset1:33
	ds_read2_b32 v[10:11], v4 offset0:66 offset1:99
	ds_read2_b32 v[12:13], v4 offset0:132 offset1:165
	ds_read2_b32 v[14:15], v4 offset0:198 offset1:231
	s_waitcnt lgkmcnt(0)
	v_cvt_pk_bf16_f32 v16, v8, v9
	v_cvt_pk_bf16_f32 v17, v10, v11
	v_cvt_pk_bf16_f32 v18, v12, v13
	v_cvt_pk_bf16_f32 v19, v14, v15
	global_store_dwordx4 v5, v[16:19], s[48:49]
	ds_read2_b32 v[8:9], v4 offset0:8 offset1:41
	ds_read2_b32 v[10:11], v4 offset0:74 offset1:107
	ds_read2_b32 v[12:13], v4 offset0:140 offset1:173
	ds_read2_b32 v[14:15], v4 offset0:206 offset1:239
	s_waitcnt lgkmcnt(0)
	v_cvt_pk_bf16_f32 v20, v8, v9
	v_cvt_pk_bf16_f32 v21, v10, v11
	v_cvt_pk_bf16_f32 v22, v12, v13
	v_cvt_pk_bf16_f32 v23, v14, v15
	v_add_u32_e32 v7, 0xc000, v5
	global_store_dwordx4 v7, v[20:23], s[48:49]
	ds_read2_b32 v[8:9], v4 offset0:16 offset1:49
	ds_read2_b32 v[10:11], v4 offset0:82 offset1:115
	ds_read2_b32 v[12:13], v4 offset0:148 offset1:181
	ds_read2_b32 v[14:15], v4 offset0:214 offset1:247
	s_waitcnt lgkmcnt(0)
	v_cvt_pk_bf16_f32 v24, v8, v9
	v_cvt_pk_bf16_f32 v25, v10, v11
	v_cvt_pk_bf16_f32 v26, v12, v13
	v_cvt_pk_bf16_f32 v27, v14, v15
	v_add_u32_e32 v7, 0x18000, v5
	global_store_dwordx4 v7, v[24:27], s[48:49]
	ds_read2_b32 v[8:9], v4 offset0:24 offset1:57
	ds_read2_b32 v[10:11], v4 offset0:90 offset1:123
	ds_read2_b32 v[12:13], v4 offset0:156 offset1:189
	ds_read2_b32 v[14:15], v4 offset0:222 offset1:255
	s_waitcnt lgkmcnt(0)
	v_cvt_pk_bf16_f32 v28, v8, v9
	v_cvt_pk_bf16_f32 v29, v10, v11
	v_cvt_pk_bf16_f32 v30, v12, v13
	v_cvt_pk_bf16_f32 v31, v14, v15
	v_add_u32_e32 v7, 0x24000, v5
	global_store_dwordx4 v7, v[28:31], s[48:49]
	s_mov_b32 s3, s0
	s_lshr_b32 s29, s3, 6
	s_and_b32 s35, s3, 63
	s_lshl_b32 s58, s29, 19
	s_lshl_b32 s59, s35, 7
	s_add_u32 s58, s58, s59
	s_add_u32 s46, s8, s58
	s_addc_u32 s47, s9, 0
	global_load_dwordx4 v[16:19], v1, s[46:47] nt
	v_add_u32_e32 v7, 0x10000, v1
	global_load_dwordx4 v[20:23], v7, s[46:47] nt
	v_add_u32_e32 v7, 0x20000, v1
	global_load_dwordx4 v[24:27], v7, s[46:47] nt
	v_add_u32_e32 v7, 0x30000, v1
	global_load_dwordx4 v[28:31], v7, s[46:47] nt
	v_add_u32_e32 v7, 0x40000, v1
	global_load_dwordx4 v[32:35], v7, s[46:47] nt
	v_add_u32_e32 v7, 0x50000, v1
	global_load_dwordx4 v[36:39], v7, s[46:47] nt
	v_add_u32_e32 v7, 0x60000, v1
	global_load_dwordx4 v[40:43], v7, s[46:47] nt
	v_add_u32_e32 v7, 0x70000, v1
	global_load_dwordx4 v[44:47], v7, s[46:47] nt
	s_waitcnt vmcnt(20)
	ds_write_b32 v3, v48
	ds_write_b32 v3, v49 offset:4
	ds_write_b32 v3, v50 offset:8
	ds_write_b32 v3, v51 offset:12
	ds_write_b32 v3, v52 offset:1056
	ds_write_b32 v3, v53 offset:1060
	ds_write_b32 v3, v54 offset:1064
	ds_write_b32 v3, v55 offset:1068
	ds_write_b32 v3, v56 offset:2112
	ds_write_b32 v3, v57 offset:2116
	ds_write_b32 v3, v58 offset:2120
	ds_write_b32 v3, v59 offset:2124
	ds_write_b32 v3, v60 offset:3168
	ds_write_b32 v3, v61 offset:3172
	ds_write_b32 v3, v62 offset:3176
	ds_write_b32 v3, v63 offset:3180
	ds_write_b32 v3, v64 offset:4224
	ds_write_b32 v3, v65 offset:4228
	ds_write_b32 v3, v66 offset:4232
	ds_write_b32 v3, v67 offset:4236
	ds_write_b32 v3, v68 offset:5280
	ds_write_b32 v3, v69 offset:5284
	ds_write_b32 v3, v70 offset:5288
	ds_write_b32 v3, v71 offset:5292
	ds_write_b32 v3, v72 offset:6336
	ds_write_b32 v3, v73 offset:6340
	ds_write_b32 v3, v74 offset:6344
	ds_write_b32 v3, v75 offset:6348
	ds_write_b32 v3, v76 offset:7392
	ds_write_b32 v3, v77 offset:7396
	ds_write_b32 v3, v78 offset:7400
	ds_write_b32 v3, v79 offset:7404
	s_waitcnt lgkmcnt(0)
	s_add_i32 s3, s0, 1024
	s_lshr_b32 s29, s3, 6
	s_and_b32 s35, s3, 63
	s_mul_i32 s58, s35, 0x30000
	s_lshl_b32 s59, s29, 7
	s_add_u32 s58, s58, s59
	s_add_u32 s48, s12, s58
	s_addc_u32 s49, s13, 0
	ds_read2_b32 v[8:9], v4 offset0:0 offset1:33
	ds_read2_b32 v[10:11], v4 offset0:66 offset1:99
	ds_read2_b32 v[12:13], v4 offset0:132 offset1:165
	ds_read2_b32 v[14:15], v4 offset0:198 offset1:231
	s_waitcnt lgkmcnt(0)
	v_cvt_pk_bf16_f32 v48, v8, v9
	v_cvt_pk_bf16_f32 v49, v10, v11
	v_cvt_pk_bf16_f32 v50, v12, v13
	v_cvt_pk_bf16_f32 v51, v14, v15
	global_store_dwordx4 v5, v[48:51], s[48:49]
	ds_read2_b32 v[8:9], v4 offset0:8 offset1:41
	ds_read2_b32 v[10:11], v4 offset0:74 offset1:107
	ds_read2_b32 v[12:13], v4 offset0:140 offset1:173
	ds_read2_b32 v[14:15], v4 offset0:206 offset1:239
	s_waitcnt lgkmcnt(0)
	v_cvt_pk_bf16_f32 v52, v8, v9
	v_cvt_pk_bf16_f32 v53, v10, v11
	v_cvt_pk_bf16_f32 v54, v12, v13
	v_cvt_pk_bf16_f32 v55, v14, v15
	v_add_u32_e32 v7, 0xc000, v5
	global_store_dwordx4 v7, v[52:55], s[48:49]
	ds_read2_b32 v[8:9], v4 offset0:16 offset1:49
	ds_read2_b32 v[10:11], v4 offset0:82 offset1:115
	ds_read2_b32 v[12:13], v4 offset0:148 offset1:181
	ds_read2_b32 v[14:15], v4 offset0:214 offset1:247
	s_waitcnt lgkmcnt(0)
	v_cvt_pk_bf16_f32 v56, v8, v9
	v_cvt_pk_bf16_f32 v57, v10, v11
	v_cvt_pk_bf16_f32 v58, v12, v13
	v_cvt_pk_bf16_f32 v59, v14, v15
	v_add_u32_e32 v7, 0x18000, v5
	global_store_dwordx4 v7, v[56:59], s[48:49]
	ds_read2_b32 v[8:9], v4 offset0:24 offset1:57
	ds_read2_b32 v[10:11], v4 offset0:90 offset1:123
	ds_read2_b32 v[12:13], v4 offset0:156 offset1:189
	ds_read2_b32 v[14:15], v4 offset0:222 offset1:255
	s_waitcnt lgkmcnt(0)
	v_cvt_pk_bf16_f32 v60, v8, v9
	v_cvt_pk_bf16_f32 v61, v10, v11
	v_cvt_pk_bf16_f32 v62, v12, v13
	v_cvt_pk_bf16_f32 v63, v14, v15
	v_add_u32_e32 v7, 0x24000, v5
	global_store_dwordx4 v7, v[60:63], s[48:49]
	s_add_i32 s3, s0, 1024
	s_lshr_b32 s29, s3, 6
	s_and_b32 s35, s3, 63
	s_lshl_b32 s58, s29, 19
	s_lshl_b32 s59, s35, 7
	s_add_u32 s58, s58, s59
	s_add_u32 s46, s8, s58
	s_addc_u32 s47, s9, 0
	global_load_dwordx4 v[48:51], v1, s[46:47] nt
	v_add_u32_e32 v7, 0x10000, v1
	global_load_dwordx4 v[52:55], v7, s[46:47] nt
	v_add_u32_e32 v7, 0x20000, v1
	global_load_dwordx4 v[56:59], v7, s[46:47] nt
	v_add_u32_e32 v7, 0x30000, v1
	global_load_dwordx4 v[60:63], v7, s[46:47] nt
	v_add_u32_e32 v7, 0x40000, v1
	global_load_dwordx4 v[64:67], v7, s[46:47] nt
	v_add_u32_e32 v7, 0x50000, v1
	global_load_dwordx4 v[68:71], v7, s[46:47] nt
	v_add_u32_e32 v7, 0x60000, v1
	global_load_dwordx4 v[72:75], v7, s[46:47] nt
	v_add_u32_e32 v7, 0x70000, v1
	global_load_dwordx4 v[76:79], v7, s[46:47] nt
	s_waitcnt vmcnt(24)
	ds_write_b32 v3, v80
	ds_write_b32 v3, v81 offset:4
	ds_write_b32 v3, v82 offset:8
	ds_write_b32 v3, v83 offset:12
	ds_write_b32 v3, v84 offset:1056
	ds_write_b32 v3, v85 offset:1060
	ds_write_b32 v3, v86 offset:1064
	ds_write_b32 v3, v87 offset:1068
	ds_write_b32 v3, v88 offset:2112
	ds_write_b32 v3, v89 offset:2116
	ds_write_b32 v3, v90 offset:2120
	ds_write_b32 v3, v91 offset:2124
	ds_write_b32 v3, v92 offset:3168
	ds_write_b32 v3, v93 offset:3172
	ds_write_b32 v3, v94 offset:3176
	ds_write_b32 v3, v95 offset:3180
	ds_write_b32 v3, v96 offset:4224
	ds_write_b32 v3, v97 offset:4228
	ds_write_b32 v3, v98 offset:4232
	ds_write_b32 v3, v99 offset:4236
	ds_write_b32 v3, v100 offset:5280
	ds_write_b32 v3, v101 offset:5284
	ds_write_b32 v3, v102 offset:5288
	ds_write_b32 v3, v103 offset:5292
	ds_write_b32 v3, v104 offset:6336
	ds_write_b32 v3, v105 offset:6340
	ds_write_b32 v3, v106 offset:6344
	ds_write_b32 v3, v107 offset:6348
	ds_write_b32 v3, v108 offset:7392
	ds_write_b32 v3, v109 offset:7396
	ds_write_b32 v3, v110 offset:7400
	ds_write_b32 v3, v111 offset:7404
	s_waitcnt lgkmcnt(0)
	s_mov_b32 s3, s0
	s_lshr_b32 s29, s3, 6
	s_and_b32 s35, s3, 63
	s_mul_i32 s58, s35, 0x30000
	s_lshl_b32 s59, s29, 7
	s_add_u32 s58, s58, s59
	s_add_u32 s58, s58, 0x1000
	s_add_u32 s48, s12, s58
	s_addc_u32 s49, s13, 0
	ds_read2_b32 v[8:9], v4 offset0:0 offset1:33
	ds_read2_b32 v[10:11], v4 offset0:66 offset1:99
	ds_read2_b32 v[12:13], v4 offset0:132 offset1:165
	ds_read2_b32 v[14:15], v4 offset0:198 offset1:231
	s_waitcnt lgkmcnt(0)
	v_cvt_pk_bf16_f32 v80, v8, v9
	v_cvt_pk_bf16_f32 v81, v10, v11
	v_cvt_pk_bf16_f32 v82, v12, v13
	v_cvt_pk_bf16_f32 v83, v14, v15
	global_store_dwordx4 v5, v[80:83], s[48:49]
	ds_read2_b32 v[8:9], v4 offset0:8 offset1:41
	ds_read2_b32 v[10:11], v4 offset0:74 offset1:107
	ds_read2_b32 v[12:13], v4 offset0:140 offset1:173
	ds_read2_b32 v[14:15], v4 offset0:206 offset1:239
	s_waitcnt lgkmcnt(0)
	v_cvt_pk_bf16_f32 v84, v8, v9
	v_cvt_pk_bf16_f32 v85, v10, v11
	v_cvt_pk_bf16_f32 v86, v12, v13
	v_cvt_pk_bf16_f32 v87, v14, v15
	v_add_u32_e32 v7, 0xc000, v5
	global_store_dwordx4 v7, v[84:87], s[48:49]
	ds_read2_b32 v[8:9], v4 offset0:16 offset1:49
	ds_read2_b32 v[10:11], v4 offset0:82 offset1:115
	ds_read2_b32 v[12:13], v4 offset0:148 offset1:181
	ds_read2_b32 v[14:15], v4 offset0:214 offset1:247
	s_waitcnt lgkmcnt(0)
	v_cvt_pk_bf16_f32 v88, v8, v9
	v_cvt_pk_bf16_f32 v89, v10, v11
	v_cvt_pk_bf16_f32 v90, v12, v13
	v_cvt_pk_bf16_f32 v91, v14, v15
	v_add_u32_e32 v7, 0x18000, v5
	global_store_dwordx4 v7, v[88:91], s[48:49]
	ds_read2_b32 v[8:9], v4 offset0:24 offset1:57
	ds_read2_b32 v[10:11], v4 offset0:90 offset1:123
	ds_read2_b32 v[12:13], v4 offset0:156 offset1:189
	ds_read2_b32 v[14:15], v4 offset0:222 offset1:255
	s_waitcnt lgkmcnt(0)
	v_cvt_pk_bf16_f32 v92, v8, v9
	v_cvt_pk_bf16_f32 v93, v10, v11
	v_cvt_pk_bf16_f32 v94, v12, v13
	v_cvt_pk_bf16_f32 v95, v14, v15
	v_add_u32_e32 v7, 0x24000, v5
	global_store_dwordx4 v7, v[92:95], s[48:49]
	s_mov_b32 s3, s0
	s_mul_i32 s29, s3, 0x1745e
	s_lshr_b32 s29, s29, 25
	s_mul_i32 s35, s29, 0x160
	s_sub_i32 s35, s3, s35
	s_mul_i32 s58, s29, 0x2c0000
	s_lshl_b32 s59, s35, 7
	s_add_u32 s58, s58, s59
	s_add_u32 s46, s10, s58
	s_addc_u32 s47, s11, 0
	global_load_dwordx4 v[80:83], v2, s[46:47] nt
	v_add_u32_e32 v7, 0x58000, v2
	global_load_dwordx4 v[84:87], v7, s[46:47] nt
	v_add_u32_e32 v7, 0xb0000, v2
	global_load_dwordx4 v[88:91], v7, s[46:47] nt
	v_add_u32_e32 v7, 0x108000, v2
	global_load_dwordx4 v[92:95], v7, s[46:47] nt
	v_add_u32_e32 v7, 0x160000, v2
	global_load_dwordx4 v[96:99], v7, s[46:47] nt
	v_add_u32_e32 v7, 0x1b8000, v2
	global_load_dwordx4 v[100:103], v7, s[46:47] nt
	v_add_u32_e32 v7, 0x210000, v2
	global_load_dwordx4 v[104:107], v7, s[46:47] nt
	v_add_u32_e32 v7, 0x268000, v2
	global_load_dwordx4 v[108:111], v7, s[46:47] nt
	s_waitcnt vmcnt(24)
	ds_write_b32 v3, v16
	ds_write_b32 v3, v17 offset:4
	ds_write_b32 v3, v18 offset:8
	ds_write_b32 v3, v19 offset:12
	ds_write_b32 v3, v20 offset:1056
	ds_write_b32 v3, v21 offset:1060
	ds_write_b32 v3, v22 offset:1064
	ds_write_b32 v3, v23 offset:1068
	ds_write_b32 v3, v24 offset:2112
	ds_write_b32 v3, v25 offset:2116
	ds_write_b32 v3, v26 offset:2120
	ds_write_b32 v3, v27 offset:2124
	ds_write_b32 v3, v28 offset:3168
	ds_write_b32 v3, v29 offset:3172
	ds_write_b32 v3, v30 offset:3176
	ds_write_b32 v3, v31 offset:3180
	ds_write_b32 v3, v32 offset:4224
	ds_write_b32 v3, v33 offset:4228
	ds_write_b32 v3, v34 offset:4232
	ds_write_b32 v3, v35 offset:4236
	ds_write_b32 v3, v36 offset:5280
	ds_write_b32 v3, v37 offset:5284
	ds_write_b32 v3, v38 offset:5288
	ds_write_b32 v3, v39 offset:5292
	ds_write_b32 v3, v40 offset:6336
	ds_write_b32 v3, v41 offset:6340
	ds_write_b32 v3, v42 offset:6344
	ds_write_b32 v3, v43 offset:6348
	ds_write_b32 v3, v44 offset:7392
	ds_write_b32 v3, v45 offset:7396
	ds_write_b32 v3, v46 offset:7400
	ds_write_b32 v3, v47 offset:7404
	s_waitcnt lgkmcnt(0)
	s_mov_b32 s3, s0
	s_lshr_b32 s29, s3, 6
	s_and_b32 s35, s3, 63
	s_lshl_b32 s58, s35, 17
	s_lshl_b32 s59, s29, 7
	s_add_u32 s58, s58, s59
	s_add_u32 s48, s30, s58
	s_addc_u32 s49, s31, 0
	ds_read2_b32 v[8:9], v4 offset0:0 offset1:33
	ds_read2_b32 v[10:11], v4 offset0:66 offset1:99
	ds_read2_b32 v[12:13], v4 offset0:132 offset1:165
	ds_read2_b32 v[14:15], v4 offset0:198 offset1:231
	s_waitcnt lgkmcnt(0)
	v_cvt_pk_bf16_f32 v16, v8, v9
	v_cvt_pk_bf16_f32 v17, v10, v11
	v_cvt_pk_bf16_f32 v18, v12, v13
	v_cvt_pk_bf16_f32 v19, v14, v15
	global_store_dwordx4 v6, v[16:19], s[48:49]
	ds_read2_b32 v[8:9], v4 offset0:8 offset1:41
	ds_read2_b32 v[10:11], v4 offset0:74 offset1:107
	ds_read2_b32 v[12:13], v4 offset0:140 offset1:173
	ds_read2_b32 v[14:15], v4 offset0:206 offset1:239
	s_waitcnt lgkmcnt(0)
	v_cvt_pk_bf16_f32 v20, v8, v9
	v_cvt_pk_bf16_f32 v21, v10, v11
	v_cvt_pk_bf16_f32 v22, v12, v13
	v_cvt_pk_bf16_f32 v23, v14, v15
	v_add_u32_e32 v7, 0x8000, v6
	global_store_dwordx4 v7, v[20:23], s[48:49]
	ds_read2_b32 v[8:9], v4 offset0:16 offset1:49
	ds_read2_b32 v[10:11], v4 offset0:82 offset1:115
	ds_read2_b32 v[12:13], v4 offset0:148 offset1:181
	ds_read2_b32 v[14:15], v4 offset0:214 offset1:247
	s_waitcnt lgkmcnt(0)
	v_cvt_pk_bf16_f32 v24, v8, v9
	v_cvt_pk_bf16_f32 v25, v10, v11
	v_cvt_pk_bf16_f32 v26, v12, v13
	v_cvt_pk_bf16_f32 v27, v14, v15
	v_add_u32_e32 v7, 0x10000, v6
	global_store_dwordx4 v7, v[24:27], s[48:49]
	ds_read2_b32 v[8:9], v4 offset0:24 offset1:57
	ds_read2_b32 v[10:11], v4 offset0:90 offset1:123
	ds_read2_b32 v[12:13], v4 offset0:156 offset1:189
	ds_read2_b32 v[14:15], v4 offset0:222 offset1:255
	s_waitcnt lgkmcnt(0)
	v_cvt_pk_bf16_f32 v28, v8, v9
	v_cvt_pk_bf16_f32 v29, v10, v11
	v_cvt_pk_bf16_f32 v30, v12, v13
	v_cvt_pk_bf16_f32 v31, v14, v15
	v_add_u32_e32 v7, 0x18000, v6
	global_store_dwordx4 v7, v[28:31], s[48:49]
	s_add_i32 s3, s0, 1024
	s_mul_i32 s29, s3, 0x1745e
	s_lshr_b32 s29, s29, 25
	s_mul_i32 s35, s29, 0x160
	s_sub_i32 s35, s3, s35
	s_mul_i32 s58, s29, 0x2c0000
	s_lshl_b32 s59, s35, 7
	s_add_u32 s58, s58, s59
	s_add_u32 s46, s10, s58
	s_addc_u32 s47, s11, 0
	global_load_dwordx4 v[16:19], v2, s[46:47] nt
	v_add_u32_e32 v7, 0x58000, v2
	global_load_dwordx4 v[20:23], v7, s[46:47] nt
	v_add_u32_e32 v7, 0xb0000, v2
	global_load_dwordx4 v[24:27], v7, s[46:47] nt
	v_add_u32_e32 v7, 0x108000, v2
	global_load_dwordx4 v[28:31], v7, s[46:47] nt
	v_add_u32_e32 v7, 0x160000, v2
	global_load_dwordx4 v[32:35], v7, s[46:47] nt
	v_add_u32_e32 v7, 0x1b8000, v2
	global_load_dwordx4 v[36:39], v7, s[46:47] nt
	v_add_u32_e32 v7, 0x210000, v2
	global_load_dwordx4 v[40:43], v7, s[46:47] nt
	v_add_u32_e32 v7, 0x268000, v2
	global_load_dwordx4 v[44:47], v7, s[46:47] nt
	s_waitcnt vmcnt(24)
	ds_write_b32 v3, v48
	ds_write_b32 v3, v49 offset:4
	ds_write_b32 v3, v50 offset:8
	ds_write_b32 v3, v51 offset:12
	ds_write_b32 v3, v52 offset:1056
	ds_write_b32 v3, v53 offset:1060
	ds_write_b32 v3, v54 offset:1064
	ds_write_b32 v3, v55 offset:1068
	ds_write_b32 v3, v56 offset:2112
	ds_write_b32 v3, v57 offset:2116
	ds_write_b32 v3, v58 offset:2120
	ds_write_b32 v3, v59 offset:2124
	ds_write_b32 v3, v60 offset:3168
	ds_write_b32 v3, v61 offset:3172
	ds_write_b32 v3, v62 offset:3176
	ds_write_b32 v3, v63 offset:3180
	ds_write_b32 v3, v64 offset:4224
	ds_write_b32 v3, v65 offset:4228
	ds_write_b32 v3, v66 offset:4232
	ds_write_b32 v3, v67 offset:4236
	ds_write_b32 v3, v68 offset:5280
	ds_write_b32 v3, v69 offset:5284
	ds_write_b32 v3, v70 offset:5288
	ds_write_b32 v3, v71 offset:5292
	ds_write_b32 v3, v72 offset:6336
	ds_write_b32 v3, v73 offset:6340
	ds_write_b32 v3, v74 offset:6344
	ds_write_b32 v3, v75 offset:6348
	ds_write_b32 v3, v76 offset:7392
	ds_write_b32 v3, v77 offset:7396
	ds_write_b32 v3, v78 offset:7400
	ds_write_b32 v3, v79 offset:7404
	s_waitcnt lgkmcnt(0)
	s_add_i32 s3, s0, 1024
	s_lshr_b32 s29, s3, 6
	s_and_b32 s35, s3, 63
	s_lshl_b32 s58, s35, 17
	s_lshl_b32 s59, s29, 7
	s_add_u32 s58, s58, s59
	s_add_u32 s48, s30, s58
	s_addc_u32 s49, s31, 0
	ds_read2_b32 v[8:9], v4 offset0:0 offset1:33
	ds_read2_b32 v[10:11], v4 offset0:66 offset1:99
	ds_read2_b32 v[12:13], v4 offset0:132 offset1:165
	ds_read2_b32 v[14:15], v4 offset0:198 offset1:231
	s_waitcnt lgkmcnt(0)
	v_cvt_pk_bf16_f32 v48, v8, v9
	v_cvt_pk_bf16_f32 v49, v10, v11
	v_cvt_pk_bf16_f32 v50, v12, v13
	v_cvt_pk_bf16_f32 v51, v14, v15
	global_store_dwordx4 v6, v[48:51], s[48:49]
	ds_read2_b32 v[8:9], v4 offset0:8 offset1:41
	ds_read2_b32 v[10:11], v4 offset0:74 offset1:107
	ds_read2_b32 v[12:13], v4 offset0:140 offset1:173
	ds_read2_b32 v[14:15], v4 offset0:206 offset1:239
	s_waitcnt lgkmcnt(0)
	v_cvt_pk_bf16_f32 v52, v8, v9
	v_cvt_pk_bf16_f32 v53, v10, v11
	v_cvt_pk_bf16_f32 v54, v12, v13
	v_cvt_pk_bf16_f32 v55, v14, v15
	v_add_u32_e32 v7, 0x8000, v6
	global_store_dwordx4 v7, v[52:55], s[48:49]
	ds_read2_b32 v[8:9], v4 offset0:16 offset1:49
	ds_read2_b32 v[10:11], v4 offset0:82 offset1:115
	ds_read2_b32 v[12:13], v4 offset0:148 offset1:181
	ds_read2_b32 v[14:15], v4 offset0:214 offset1:247
	s_waitcnt lgkmcnt(0)
	v_cvt_pk_bf16_f32 v56, v8, v9
	v_cvt_pk_bf16_f32 v57, v10, v11
	v_cvt_pk_bf16_f32 v58, v12, v13
	v_cvt_pk_bf16_f32 v59, v14, v15
	v_add_u32_e32 v7, 0x10000, v6
	global_store_dwordx4 v7, v[56:59], s[48:49]
	ds_read2_b32 v[8:9], v4 offset0:24 offset1:57
	ds_read2_b32 v[10:11], v4 offset0:90 offset1:123
	ds_read2_b32 v[12:13], v4 offset0:156 offset1:189
	ds_read2_b32 v[14:15], v4 offset0:222 offset1:255
	s_waitcnt lgkmcnt(0)
	v_cvt_pk_bf16_f32 v60, v8, v9
	v_cvt_pk_bf16_f32 v61, v10, v11
	v_cvt_pk_bf16_f32 v62, v12, v13
	v_cvt_pk_bf16_f32 v63, v14, v15
	v_add_u32_e32 v7, 0x18000, v6
	global_store_dwordx4 v7, v[60:63], s[48:49]
	s_add_i32 s3, s0, 2048
	s_mul_i32 s29, s3, 0x1745e
	s_lshr_b32 s29, s29, 25
	s_mul_i32 s35, s29, 0x160
	s_sub_i32 s35, s3, s35
	s_mul_i32 s58, s29, 0x2c0000
	s_lshl_b32 s59, s35, 7
	s_add_u32 s58, s58, s59
	s_add_u32 s46, s10, s58
	s_addc_u32 s47, s11, 0
	global_load_dwordx4 v[48:51], v2, s[46:47] nt
	v_add_u32_e32 v7, 0x58000, v2
	global_load_dwordx4 v[52:55], v7, s[46:47] nt
	v_add_u32_e32 v7, 0xb0000, v2
	global_load_dwordx4 v[56:59], v7, s[46:47] nt
	v_add_u32_e32 v7, 0x108000, v2
	global_load_dwordx4 v[60:63], v7, s[46:47] nt
	v_add_u32_e32 v7, 0x160000, v2
	global_load_dwordx4 v[64:67], v7, s[46:47] nt
	v_add_u32_e32 v7, 0x1b8000, v2
	global_load_dwordx4 v[68:71], v7, s[46:47] nt
	v_add_u32_e32 v7, 0x210000, v2
	global_load_dwordx4 v[72:75], v7, s[46:47] nt
	v_add_u32_e32 v7, 0x268000, v2
	global_load_dwordx4 v[76:79], v7, s[46:47] nt
	s_waitcnt vmcnt(24)
	ds_write_b32 v3, v80
	ds_write_b32 v3, v81 offset:4
	ds_write_b32 v3, v82 offset:8
	ds_write_b32 v3, v83 offset:12
	ds_write_b32 v3, v84 offset:1056
	ds_write_b32 v3, v85 offset:1060
	ds_write_b32 v3, v86 offset:1064
	ds_write_b32 v3, v87 offset:1068
	ds_write_b32 v3, v88 offset:2112
	ds_write_b32 v3, v89 offset:2116
	ds_write_b32 v3, v90 offset:2120
	ds_write_b32 v3, v91 offset:2124
	ds_write_b32 v3, v92 offset:3168
	ds_write_b32 v3, v93 offset:3172
	ds_write_b32 v3, v94 offset:3176
	ds_write_b32 v3, v95 offset:3180
	ds_write_b32 v3, v96 offset:4224
	ds_write_b32 v3, v97 offset:4228
	ds_write_b32 v3, v98 offset:4232
	ds_write_b32 v3, v99 offset:4236
	ds_write_b32 v3, v100 offset:5280
	ds_write_b32 v3, v101 offset:5284
	ds_write_b32 v3, v102 offset:5288
	ds_write_b32 v3, v103 offset:5292
	ds_write_b32 v3, v104 offset:6336
	ds_write_b32 v3, v105 offset:6340
	ds_write_b32 v3, v106 offset:6344
	ds_write_b32 v3, v107 offset:6348
	ds_write_b32 v3, v108 offset:7392
	ds_write_b32 v3, v109 offset:7396
	ds_write_b32 v3, v110 offset:7400
	ds_write_b32 v3, v111 offset:7404
	s_waitcnt lgkmcnt(0)
	s_mov_b32 s3, s0
	s_mul_i32 s29, s3, 0x1745e
	s_lshr_b32 s29, s29, 25
	s_mul_i32 s35, s29, 0x160
	s_sub_i32 s35, s3, s35
	s_lshl_b32 s58, s35, 17
	s_lshl_b32 s59, s29, 7
	s_add_u32 s58, s58, s59
	s_add_u32 s48, s42, s58
	s_addc_u32 s49, s43, 0
	ds_read2_b32 v[8:9], v4 offset0:0 offset1:33
	ds_read2_b32 v[10:11], v4 offset0:66 offset1:99
	ds_read2_b32 v[12:13], v4 offset0:132 offset1:165
	ds_read2_b32 v[14:15], v4 offset0:198 offset1:231
	s_waitcnt lgkmcnt(0)
	v_cvt_pk_bf16_f32 v80, v8, v9
	v_cvt_pk_bf16_f32 v81, v10, v11
	v_cvt_pk_bf16_f32 v82, v12, v13
	v_cvt_pk_bf16_f32 v83, v14, v15
	global_store_dwordx4 v6, v[80:83], s[48:49]
	ds_read2_b32 v[8:9], v4 offset0:8 offset1:41
	ds_read2_b32 v[10:11], v4 offset0:74 offset1:107
	ds_read2_b32 v[12:13], v4 offset0:140 offset1:173
	ds_read2_b32 v[14:15], v4 offset0:206 offset1:239
	s_waitcnt lgkmcnt(0)
	v_cvt_pk_bf16_f32 v84, v8, v9
	v_cvt_pk_bf16_f32 v85, v10, v11
	v_cvt_pk_bf16_f32 v86, v12, v13
	v_cvt_pk_bf16_f32 v87, v14, v15
	v_add_u32_e32 v7, 0x8000, v6
	global_store_dwordx4 v7, v[84:87], s[48:49]
	ds_read2_b32 v[8:9], v4 offset0:16 offset1:49
	ds_read2_b32 v[10:11], v4 offset0:82 offset1:115
	ds_read2_b32 v[12:13], v4 offset0:148 offset1:181
	ds_read2_b32 v[14:15], v4 offset0:214 offset1:247
	s_waitcnt lgkmcnt(0)
	v_cvt_pk_bf16_f32 v88, v8, v9
	v_cvt_pk_bf16_f32 v89, v10, v11
	v_cvt_pk_bf16_f32 v90, v12, v13
	v_cvt_pk_bf16_f32 v91, v14, v15
	v_add_u32_e32 v7, 0x10000, v6
	global_store_dwordx4 v7, v[88:91], s[48:49]
	ds_read2_b32 v[8:9], v4 offset0:24 offset1:57
	ds_read2_b32 v[10:11], v4 offset0:90 offset1:123
	ds_read2_b32 v[12:13], v4 offset0:156 offset1:189
	ds_read2_b32 v[14:15], v4 offset0:222 offset1:255
	s_waitcnt lgkmcnt(0)
	v_cvt_pk_bf16_f32 v92, v8, v9
	v_cvt_pk_bf16_f32 v93, v10, v11
	v_cvt_pk_bf16_f32 v94, v12, v13
	v_cvt_pk_bf16_f32 v95, v14, v15
	v_add_u32_e32 v7, 0x18000, v6
	global_store_dwordx4 v7, v[92:95], s[48:49]
	s_add_i32 s3, s0, 3072
	s_mul_i32 s29, s3, 0x1745e
	s_lshr_b32 s29, s29, 25
	s_mul_i32 s35, s29, 0x160
	s_sub_i32 s35, s3, s35
	s_mul_i32 s58, s29, 0x2c0000
	s_lshl_b32 s59, s35, 7
	s_add_u32 s58, s58, s59
	s_add_u32 s46, s10, s58
	s_addc_u32 s47, s11, 0
	global_load_dwordx4 v[80:83], v2, s[46:47] nt
	v_add_u32_e32 v7, 0x58000, v2
	global_load_dwordx4 v[84:87], v7, s[46:47] nt
	v_add_u32_e32 v7, 0xb0000, v2
	global_load_dwordx4 v[88:91], v7, s[46:47] nt
	v_add_u32_e32 v7, 0x108000, v2
	global_load_dwordx4 v[92:95], v7, s[46:47] nt
	v_add_u32_e32 v7, 0x160000, v2
	global_load_dwordx4 v[96:99], v7, s[46:47] nt
	v_add_u32_e32 v7, 0x1b8000, v2
	global_load_dwordx4 v[100:103], v7, s[46:47] nt
	v_add_u32_e32 v7, 0x210000, v2
	global_load_dwordx4 v[104:107], v7, s[46:47] nt
	v_add_u32_e32 v7, 0x268000, v2
	global_load_dwordx4 v[108:111], v7, s[46:47] nt
	s_waitcnt vmcnt(24)
	ds_write_b32 v3, v16
	ds_write_b32 v3, v17 offset:4
	ds_write_b32 v3, v18 offset:8
	ds_write_b32 v3, v19 offset:12
	ds_write_b32 v3, v20 offset:1056
	ds_write_b32 v3, v21 offset:1060
	ds_write_b32 v3, v22 offset:1064
	ds_write_b32 v3, v23 offset:1068
	ds_write_b32 v3, v24 offset:2112
	ds_write_b32 v3, v25 offset:2116
	ds_write_b32 v3, v26 offset:2120
	ds_write_b32 v3, v27 offset:2124
	ds_write_b32 v3, v28 offset:3168
	ds_write_b32 v3, v29 offset:3172
	ds_write_b32 v3, v30 offset:3176
	ds_write_b32 v3, v31 offset:3180
	ds_write_b32 v3, v32 offset:4224
	ds_write_b32 v3, v33 offset:4228
	ds_write_b32 v3, v34 offset:4232
	ds_write_b32 v3, v35 offset:4236
	ds_write_b32 v3, v36 offset:5280
	ds_write_b32 v3, v37 offset:5284
	ds_write_b32 v3, v38 offset:5288
	ds_write_b32 v3, v39 offset:5292
	ds_write_b32 v3, v40 offset:6336
	ds_write_b32 v3, v41 offset:6340
	ds_write_b32 v3, v42 offset:6344
	ds_write_b32 v3, v43 offset:6348
	ds_write_b32 v3, v44 offset:7392
	ds_write_b32 v3, v45 offset:7396
	ds_write_b32 v3, v46 offset:7400
	ds_write_b32 v3, v47 offset:7404
	s_waitcnt lgkmcnt(0)
	s_add_i32 s3, s0, 1024
	s_mul_i32 s29, s3, 0x1745e
	s_lshr_b32 s29, s29, 25
	s_mul_i32 s35, s29, 0x160
	s_sub_i32 s35, s3, s35
	s_lshl_b32 s58, s35, 17
	s_lshl_b32 s59, s29, 7
	s_add_u32 s58, s58, s59
	s_add_u32 s48, s42, s58
	s_addc_u32 s49, s43, 0
	ds_read2_b32 v[8:9], v4 offset0:0 offset1:33
	ds_read2_b32 v[10:11], v4 offset0:66 offset1:99
	ds_read2_b32 v[12:13], v4 offset0:132 offset1:165
	ds_read2_b32 v[14:15], v4 offset0:198 offset1:231
	s_waitcnt lgkmcnt(0)
	v_cvt_pk_bf16_f32 v16, v8, v9
	v_cvt_pk_bf16_f32 v17, v10, v11
	v_cvt_pk_bf16_f32 v18, v12, v13
	v_cvt_pk_bf16_f32 v19, v14, v15
	global_store_dwordx4 v6, v[16:19], s[48:49]
	ds_read2_b32 v[8:9], v4 offset0:8 offset1:41
	ds_read2_b32 v[10:11], v4 offset0:74 offset1:107
	ds_read2_b32 v[12:13], v4 offset0:140 offset1:173
	ds_read2_b32 v[14:15], v4 offset0:206 offset1:239
	s_waitcnt lgkmcnt(0)
	v_cvt_pk_bf16_f32 v20, v8, v9
	v_cvt_pk_bf16_f32 v21, v10, v11
	v_cvt_pk_bf16_f32 v22, v12, v13
	v_cvt_pk_bf16_f32 v23, v14, v15
	v_add_u32_e32 v7, 0x8000, v6
	global_store_dwordx4 v7, v[20:23], s[48:49]
	ds_read2_b32 v[8:9], v4 offset0:16 offset1:49
	ds_read2_b32 v[10:11], v4 offset0:82 offset1:115
	ds_read2_b32 v[12:13], v4 offset0:148 offset1:181
	ds_read2_b32 v[14:15], v4 offset0:214 offset1:247
	s_waitcnt lgkmcnt(0)
	v_cvt_pk_bf16_f32 v24, v8, v9
	v_cvt_pk_bf16_f32 v25, v10, v11
	v_cvt_pk_bf16_f32 v26, v12, v13
	v_cvt_pk_bf16_f32 v27, v14, v15
	v_add_u32_e32 v7, 0x10000, v6
	global_store_dwordx4 v7, v[24:27], s[48:49]
	ds_read2_b32 v[8:9], v4 offset0:24 offset1:57
	ds_read2_b32 v[10:11], v4 offset0:90 offset1:123
	ds_read2_b32 v[12:13], v4 offset0:156 offset1:189
	ds_read2_b32 v[14:15], v4 offset0:222 offset1:255
	s_waitcnt lgkmcnt(0)
	v_cvt_pk_bf16_f32 v28, v8, v9
	v_cvt_pk_bf16_f32 v29, v10, v11
	v_cvt_pk_bf16_f32 v30, v12, v13
	v_cvt_pk_bf16_f32 v31, v14, v15
	v_add_u32_e32 v7, 0x18000, v6
	global_store_dwordx4 v7, v[28:31], s[48:49]
	s_add_i32 s3, s0, 4096
	s_mul_i32 s29, s3, 0x1745e
	s_lshr_b32 s29, s29, 25
	s_mul_i32 s35, s29, 0x160
	s_sub_i32 s35, s3, s35
	s_mul_i32 s58, s29, 0x2c0000
	s_lshl_b32 s59, s35, 7
	s_add_u32 s58, s58, s59
	s_add_u32 s46, s10, s58
	s_addc_u32 s47, s11, 0
	global_load_dwordx4 v[16:19], v2, s[46:47] nt
	v_add_u32_e32 v7, 0x58000, v2
	global_load_dwordx4 v[20:23], v7, s[46:47] nt
	v_add_u32_e32 v7, 0xb0000, v2
	global_load_dwordx4 v[24:27], v7, s[46:47] nt
	v_add_u32_e32 v7, 0x108000, v2
	global_load_dwordx4 v[28:31], v7, s[46:47] nt
	v_add_u32_e32 v7, 0x160000, v2
	global_load_dwordx4 v[32:35], v7, s[46:47] nt
	v_add_u32_e32 v7, 0x1b8000, v2
	global_load_dwordx4 v[36:39], v7, s[46:47] nt
	v_add_u32_e32 v7, 0x210000, v2
	global_load_dwordx4 v[40:43], v7, s[46:47] nt
	v_add_u32_e32 v7, 0x268000, v2
	global_load_dwordx4 v[44:47], v7, s[46:47] nt
	s_waitcnt vmcnt(24)
	ds_write_b32 v3, v48
	ds_write_b32 v3, v49 offset:4
	ds_write_b32 v3, v50 offset:8
	ds_write_b32 v3, v51 offset:12
	ds_write_b32 v3, v52 offset:1056
	ds_write_b32 v3, v53 offset:1060
	ds_write_b32 v3, v54 offset:1064
	ds_write_b32 v3, v55 offset:1068
	ds_write_b32 v3, v56 offset:2112
	ds_write_b32 v3, v57 offset:2116
	ds_write_b32 v3, v58 offset:2120
	ds_write_b32 v3, v59 offset:2124
	ds_write_b32 v3, v60 offset:3168
	ds_write_b32 v3, v61 offset:3172
	ds_write_b32 v3, v62 offset:3176
	ds_write_b32 v3, v63 offset:3180
	ds_write_b32 v3, v64 offset:4224
	ds_write_b32 v3, v65 offset:4228
	ds_write_b32 v3, v66 offset:4232
	ds_write_b32 v3, v67 offset:4236
	ds_write_b32 v3, v68 offset:5280
	ds_write_b32 v3, v69 offset:5284
	ds_write_b32 v3, v70 offset:5288
	ds_write_b32 v3, v71 offset:5292
	ds_write_b32 v3, v72 offset:6336
	ds_write_b32 v3, v73 offset:6340
	ds_write_b32 v3, v74 offset:6344
	ds_write_b32 v3, v75 offset:6348
	ds_write_b32 v3, v76 offset:7392
	ds_write_b32 v3, v77 offset:7396
	ds_write_b32 v3, v78 offset:7400
	ds_write_b32 v3, v79 offset:7404
	s_waitcnt lgkmcnt(0)
	s_add_i32 s3, s0, 2048
	s_mul_i32 s29, s3, 0x1745e
	s_lshr_b32 s29, s29, 25
	s_mul_i32 s35, s29, 0x160
	s_sub_i32 s35, s3, s35
	s_lshl_b32 s58, s35, 17
	s_lshl_b32 s59, s29, 7
	s_add_u32 s58, s58, s59
	s_add_u32 s48, s42, s58
	s_addc_u32 s49, s43, 0
	ds_read2_b32 v[8:9], v4 offset0:0 offset1:33
	ds_read2_b32 v[10:11], v4 offset0:66 offset1:99
	ds_read2_b32 v[12:13], v4 offset0:132 offset1:165
	ds_read2_b32 v[14:15], v4 offset0:198 offset1:231
	s_waitcnt lgkmcnt(0)
	v_cvt_pk_bf16_f32 v48, v8, v9
	v_cvt_pk_bf16_f32 v49, v10, v11
	v_cvt_pk_bf16_f32 v50, v12, v13
	v_cvt_pk_bf16_f32 v51, v14, v15
	global_store_dwordx4 v6, v[48:51], s[48:49]
	ds_read2_b32 v[8:9], v4 offset0:8 offset1:41
	ds_read2_b32 v[10:11], v4 offset0:74 offset1:107
	ds_read2_b32 v[12:13], v4 offset0:140 offset1:173
	ds_read2_b32 v[14:15], v4 offset0:206 offset1:239
	s_waitcnt lgkmcnt(0)
	v_cvt_pk_bf16_f32 v52, v8, v9
	v_cvt_pk_bf16_f32 v53, v10, v11
	v_cvt_pk_bf16_f32 v54, v12, v13
	v_cvt_pk_bf16_f32 v55, v14, v15
	v_add_u32_e32 v7, 0x8000, v6
	global_store_dwordx4 v7, v[52:55], s[48:49]
	ds_read2_b32 v[8:9], v4 offset0:16 offset1:49
	ds_read2_b32 v[10:11], v4 offset0:82 offset1:115
	ds_read2_b32 v[12:13], v4 offset0:148 offset1:181
	ds_read2_b32 v[14:15], v4 offset0:214 offset1:247
	s_waitcnt lgkmcnt(0)
	v_cvt_pk_bf16_f32 v56, v8, v9
	v_cvt_pk_bf16_f32 v57, v10, v11
	v_cvt_pk_bf16_f32 v58, v12, v13
	v_cvt_pk_bf16_f32 v59, v14, v15
	v_add_u32_e32 v7, 0x10000, v6
	global_store_dwordx4 v7, v[56:59], s[48:49]
	ds_read2_b32 v[8:9], v4 offset0:24 offset1:57
	ds_read2_b32 v[10:11], v4 offset0:90 offset1:123
	ds_read2_b32 v[12:13], v4 offset0:156 offset1:189
	ds_read2_b32 v[14:15], v4 offset0:222 offset1:255
	s_waitcnt lgkmcnt(0)
	v_cvt_pk_bf16_f32 v60, v8, v9
	v_cvt_pk_bf16_f32 v61, v10, v11
	v_cvt_pk_bf16_f32 v62, v12, v13
	v_cvt_pk_bf16_f32 v63, v14, v15
	v_add_u32_e32 v7, 0x18000, v6
	global_store_dwordx4 v7, v[60:63], s[48:49]
	s_add_i32 s3, s0, 5120
	s_mul_i32 s29, s3, 0x1745e
	s_lshr_b32 s29, s29, 25
	s_mul_i32 s35, s29, 0x160
	s_sub_i32 s35, s3, s35
	s_mul_i32 s58, s29, 0x2c0000
	s_lshl_b32 s59, s35, 7
	s_add_u32 s58, s58, s59
	s_add_u32 s46, s10, s58
	s_addc_u32 s47, s11, 0
	global_load_dwordx4 v[48:51], v2, s[46:47] nt
	v_add_u32_e32 v7, 0x58000, v2
	global_load_dwordx4 v[52:55], v7, s[46:47] nt
	v_add_u32_e32 v7, 0xb0000, v2
	global_load_dwordx4 v[56:59], v7, s[46:47] nt
	v_add_u32_e32 v7, 0x108000, v2
	global_load_dwordx4 v[60:63], v7, s[46:47] nt
	v_add_u32_e32 v7, 0x160000, v2
	global_load_dwordx4 v[64:67], v7, s[46:47] nt
	v_add_u32_e32 v7, 0x1b8000, v2
	global_load_dwordx4 v[68:71], v7, s[46:47] nt
	v_add_u32_e32 v7, 0x210000, v2
	global_load_dwordx4 v[72:75], v7, s[46:47] nt
	v_add_u32_e32 v7, 0x268000, v2
	global_load_dwordx4 v[76:79], v7, s[46:47] nt
	s_waitcnt vmcnt(24)
	ds_write_b32 v3, v80
	ds_write_b32 v3, v81 offset:4
	ds_write_b32 v3, v82 offset:8
	ds_write_b32 v3, v83 offset:12
	ds_write_b32 v3, v84 offset:1056
	ds_write_b32 v3, v85 offset:1060
	ds_write_b32 v3, v86 offset:1064
	ds_write_b32 v3, v87 offset:1068
	ds_write_b32 v3, v88 offset:2112
	ds_write_b32 v3, v89 offset:2116
	ds_write_b32 v3, v90 offset:2120
	ds_write_b32 v3, v91 offset:2124
	ds_write_b32 v3, v92 offset:3168
	ds_write_b32 v3, v93 offset:3172
	ds_write_b32 v3, v94 offset:3176
	ds_write_b32 v3, v95 offset:3180
	ds_write_b32 v3, v96 offset:4224
	ds_write_b32 v3, v97 offset:4228
	ds_write_b32 v3, v98 offset:4232
	ds_write_b32 v3, v99 offset:4236
	ds_write_b32 v3, v100 offset:5280
	ds_write_b32 v3, v101 offset:5284
	ds_write_b32 v3, v102 offset:5288
	ds_write_b32 v3, v103 offset:5292
	ds_write_b32 v3, v104 offset:6336
	ds_write_b32 v3, v105 offset:6340
	ds_write_b32 v3, v106 offset:6344
	ds_write_b32 v3, v107 offset:6348
	ds_write_b32 v3, v108 offset:7392
	ds_write_b32 v3, v109 offset:7396
	ds_write_b32 v3, v110 offset:7400
	ds_write_b32 v3, v111 offset:7404
	s_waitcnt lgkmcnt(0)
	s_add_i32 s3, s0, 3072
	s_mul_i32 s29, s3, 0x1745e
	s_lshr_b32 s29, s29, 25
	s_mul_i32 s35, s29, 0x160
	s_sub_i32 s35, s3, s35
	s_lshl_b32 s58, s35, 17
	s_lshl_b32 s59, s29, 7
	s_add_u32 s58, s58, s59
	s_add_u32 s48, s42, s58
	s_addc_u32 s49, s43, 0
	ds_read2_b32 v[8:9], v4 offset0:0 offset1:33
	ds_read2_b32 v[10:11], v4 offset0:66 offset1:99
	ds_read2_b32 v[12:13], v4 offset0:132 offset1:165
	ds_read2_b32 v[14:15], v4 offset0:198 offset1:231
	s_waitcnt lgkmcnt(0)
	v_cvt_pk_bf16_f32 v80, v8, v9
	v_cvt_pk_bf16_f32 v81, v10, v11
	v_cvt_pk_bf16_f32 v82, v12, v13
	v_cvt_pk_bf16_f32 v83, v14, v15
	global_store_dwordx4 v6, v[80:83], s[48:49]
	ds_read2_b32 v[8:9], v4 offset0:8 offset1:41
	ds_read2_b32 v[10:11], v4 offset0:74 offset1:107
	ds_read2_b32 v[12:13], v4 offset0:140 offset1:173
	ds_read2_b32 v[14:15], v4 offset0:206 offset1:239
	s_waitcnt lgkmcnt(0)
	v_cvt_pk_bf16_f32 v84, v8, v9
	v_cvt_pk_bf16_f32 v85, v10, v11
	v_cvt_pk_bf16_f32 v86, v12, v13
	v_cvt_pk_bf16_f32 v87, v14, v15
	v_add_u32_e32 v7, 0x8000, v6
	global_store_dwordx4 v7, v[84:87], s[48:49]
	ds_read2_b32 v[8:9], v4 offset0:16 offset1:49
	ds_read2_b32 v[10:11], v4 offset0:82 offset1:115
	ds_read2_b32 v[12:13], v4 offset0:148 offset1:181
	ds_read2_b32 v[14:15], v4 offset0:214 offset1:247
	s_waitcnt lgkmcnt(0)
	v_cvt_pk_bf16_f32 v88, v8, v9
	v_cvt_pk_bf16_f32 v89, v10, v11
	v_cvt_pk_bf16_f32 v90, v12, v13
	v_cvt_pk_bf16_f32 v91, v14, v15
	v_add_u32_e32 v7, 0x10000, v6
	global_store_dwordx4 v7, v[88:91], s[48:49]
	ds_read2_b32 v[8:9], v4 offset0:24 offset1:57
	ds_read2_b32 v[10:11], v4 offset0:90 offset1:123
	ds_read2_b32 v[12:13], v4 offset0:156 offset1:189
	ds_read2_b32 v[14:15], v4 offset0:222 offset1:255
	s_waitcnt lgkmcnt(0)
	v_cvt_pk_bf16_f32 v92, v8, v9
	v_cvt_pk_bf16_f32 v93, v10, v11
	v_cvt_pk_bf16_f32 v94, v12, v13
	v_cvt_pk_bf16_f32 v95, v14, v15
	v_add_u32_e32 v7, 0x18000, v6
	global_store_dwordx4 v7, v[92:95], s[48:49]
	s_add_i32 s3, s0, 6144
	s_mul_i32 s29, s3, 0x1745e
	s_lshr_b32 s29, s29, 25
	s_mul_i32 s35, s29, 0x160
	s_sub_i32 s35, s3, s35
	s_mul_i32 s58, s29, 0x2c0000
	s_lshl_b32 s59, s35, 7
	s_add_u32 s58, s58, s59
	s_add_u32 s46, s10, s58
	s_addc_u32 s47, s11, 0
	global_load_dwordx4 v[80:83], v2, s[46:47] nt
	v_add_u32_e32 v7, 0x58000, v2
	global_load_dwordx4 v[84:87], v7, s[46:47] nt
	v_add_u32_e32 v7, 0xb0000, v2
	global_load_dwordx4 v[88:91], v7, s[46:47] nt
	v_add_u32_e32 v7, 0x108000, v2
	global_load_dwordx4 v[92:95], v7, s[46:47] nt
	v_add_u32_e32 v7, 0x160000, v2
	global_load_dwordx4 v[96:99], v7, s[46:47] nt
	v_add_u32_e32 v7, 0x1b8000, v2
	global_load_dwordx4 v[100:103], v7, s[46:47] nt
	v_add_u32_e32 v7, 0x210000, v2
	global_load_dwordx4 v[104:107], v7, s[46:47] nt
	v_add_u32_e32 v7, 0x268000, v2
	global_load_dwordx4 v[108:111], v7, s[46:47] nt
	s_waitcnt vmcnt(24)
	ds_write_b32 v3, v16
	ds_write_b32 v3, v17 offset:4
	ds_write_b32 v3, v18 offset:8
	ds_write_b32 v3, v19 offset:12
	ds_write_b32 v3, v20 offset:1056
	ds_write_b32 v3, v21 offset:1060
	ds_write_b32 v3, v22 offset:1064
	ds_write_b32 v3, v23 offset:1068
	ds_write_b32 v3, v24 offset:2112
	ds_write_b32 v3, v25 offset:2116
	ds_write_b32 v3, v26 offset:2120
	ds_write_b32 v3, v27 offset:2124
	ds_write_b32 v3, v28 offset:3168
	ds_write_b32 v3, v29 offset:3172
	ds_write_b32 v3, v30 offset:3176
	ds_write_b32 v3, v31 offset:3180
	ds_write_b32 v3, v32 offset:4224
	ds_write_b32 v3, v33 offset:4228
	ds_write_b32 v3, v34 offset:4232
	ds_write_b32 v3, v35 offset:4236
	ds_write_b32 v3, v36 offset:5280
	ds_write_b32 v3, v37 offset:5284
	ds_write_b32 v3, v38 offset:5288
	ds_write_b32 v3, v39 offset:5292
	ds_write_b32 v3, v40 offset:6336
	ds_write_b32 v3, v41 offset:6340
	ds_write_b32 v3, v42 offset:6344
	ds_write_b32 v3, v43 offset:6348
	ds_write_b32 v3, v44 offset:7392
	ds_write_b32 v3, v45 offset:7396
	ds_write_b32 v3, v46 offset:7400
	ds_write_b32 v3, v47 offset:7404
	s_waitcnt lgkmcnt(0)
	s_add_i32 s3, s0, 4096
	s_mul_i32 s29, s3, 0x1745e
	s_lshr_b32 s29, s29, 25
	s_mul_i32 s35, s29, 0x160
	s_sub_i32 s35, s3, s35
	s_lshl_b32 s58, s35, 17
	s_lshl_b32 s59, s29, 7
	s_add_u32 s58, s58, s59
	s_add_u32 s48, s42, s58
	s_addc_u32 s49, s43, 0
	ds_read2_b32 v[8:9], v4 offset0:0 offset1:33
	ds_read2_b32 v[10:11], v4 offset0:66 offset1:99
	ds_read2_b32 v[12:13], v4 offset0:132 offset1:165
	ds_read2_b32 v[14:15], v4 offset0:198 offset1:231
	s_waitcnt lgkmcnt(0)
	v_cvt_pk_bf16_f32 v16, v8, v9
	v_cvt_pk_bf16_f32 v17, v10, v11
	v_cvt_pk_bf16_f32 v18, v12, v13
	v_cvt_pk_bf16_f32 v19, v14, v15
	global_store_dwordx4 v6, v[16:19], s[48:49]
	ds_read2_b32 v[8:9], v4 offset0:8 offset1:41
	ds_read2_b32 v[10:11], v4 offset0:74 offset1:107
	ds_read2_b32 v[12:13], v4 offset0:140 offset1:173
	ds_read2_b32 v[14:15], v4 offset0:206 offset1:239
	s_waitcnt lgkmcnt(0)
	v_cvt_pk_bf16_f32 v20, v8, v9
	v_cvt_pk_bf16_f32 v21, v10, v11
	v_cvt_pk_bf16_f32 v22, v12, v13
	v_cvt_pk_bf16_f32 v23, v14, v15
	v_add_u32_e32 v7, 0x8000, v6
	global_store_dwordx4 v7, v[20:23], s[48:49]
	ds_read2_b32 v[8:9], v4 offset0:16 offset1:49
	ds_read2_b32 v[10:11], v4 offset0:82 offset1:115
	ds_read2_b32 v[12:13], v4 offset0:148 offset1:181
	ds_read2_b32 v[14:15], v4 offset0:214 offset1:247
	s_waitcnt lgkmcnt(0)
	v_cvt_pk_bf16_f32 v24, v8, v9
	v_cvt_pk_bf16_f32 v25, v10, v11
	v_cvt_pk_bf16_f32 v26, v12, v13
	v_cvt_pk_bf16_f32 v27, v14, v15
	v_add_u32_e32 v7, 0x10000, v6
	global_store_dwordx4 v7, v[24:27], s[48:49]
	ds_read2_b32 v[8:9], v4 offset0:24 offset1:57
	ds_read2_b32 v[10:11], v4 offset0:90 offset1:123
	ds_read2_b32 v[12:13], v4 offset0:156 offset1:189
	ds_read2_b32 v[14:15], v4 offset0:222 offset1:255
	s_waitcnt lgkmcnt(0)
	v_cvt_pk_bf16_f32 v28, v8, v9
	v_cvt_pk_bf16_f32 v29, v10, v11
	v_cvt_pk_bf16_f32 v30, v12, v13
	v_cvt_pk_bf16_f32 v31, v14, v15
	v_add_u32_e32 v7, 0x18000, v6
	global_store_dwordx4 v7, v[28:31], s[48:49]
	s_add_i32 s3, s0, 7168
	s_mul_i32 s29, s3, 0x1745e
	s_lshr_b32 s29, s29, 25
	s_mul_i32 s35, s29, 0x160
	s_sub_i32 s35, s3, s35
	s_mul_i32 s58, s29, 0x2c0000
	s_lshl_b32 s59, s35, 7
	s_add_u32 s58, s58, s59
	s_add_u32 s46, s10, s58
	s_addc_u32 s47, s11, 0
	global_load_dwordx4 v[16:19], v2, s[46:47] nt
	v_add_u32_e32 v7, 0x58000, v2
	global_load_dwordx4 v[20:23], v7, s[46:47] nt
	v_add_u32_e32 v7, 0xb0000, v2
	global_load_dwordx4 v[24:27], v7, s[46:47] nt
	v_add_u32_e32 v7, 0x108000, v2
	global_load_dwordx4 v[28:31], v7, s[46:47] nt
	v_add_u32_e32 v7, 0x160000, v2
	global_load_dwordx4 v[32:35], v7, s[46:47] nt
	v_add_u32_e32 v7, 0x1b8000, v2
	global_load_dwordx4 v[36:39], v7, s[46:47] nt
	v_add_u32_e32 v7, 0x210000, v2
	global_load_dwordx4 v[40:43], v7, s[46:47] nt
	v_add_u32_e32 v7, 0x268000, v2
	global_load_dwordx4 v[44:47], v7, s[46:47] nt
	s_waitcnt vmcnt(24)
	ds_write_b32 v3, v48
	ds_write_b32 v3, v49 offset:4
	ds_write_b32 v3, v50 offset:8
	ds_write_b32 v3, v51 offset:12
	ds_write_b32 v3, v52 offset:1056
	ds_write_b32 v3, v53 offset:1060
	ds_write_b32 v3, v54 offset:1064
	ds_write_b32 v3, v55 offset:1068
	ds_write_b32 v3, v56 offset:2112
	ds_write_b32 v3, v57 offset:2116
	ds_write_b32 v3, v58 offset:2120
	ds_write_b32 v3, v59 offset:2124
	ds_write_b32 v3, v60 offset:3168
	ds_write_b32 v3, v61 offset:3172
	ds_write_b32 v3, v62 offset:3176
	ds_write_b32 v3, v63 offset:3180
	ds_write_b32 v3, v64 offset:4224
	ds_write_b32 v3, v65 offset:4228
	ds_write_b32 v3, v66 offset:4232
	ds_write_b32 v3, v67 offset:4236
	ds_write_b32 v3, v68 offset:5280
	ds_write_b32 v3, v69 offset:5284
	ds_write_b32 v3, v70 offset:5288
	ds_write_b32 v3, v71 offset:5292
	ds_write_b32 v3, v72 offset:6336
	ds_write_b32 v3, v73 offset:6340
	ds_write_b32 v3, v74 offset:6344
	ds_write_b32 v3, v75 offset:6348
	ds_write_b32 v3, v76 offset:7392
	ds_write_b32 v3, v77 offset:7396
	ds_write_b32 v3, v78 offset:7400
	ds_write_b32 v3, v79 offset:7404
	s_waitcnt lgkmcnt(0)
	s_add_i32 s3, s0, 5120
	s_mul_i32 s29, s3, 0x1745e
	s_lshr_b32 s29, s29, 25
	s_mul_i32 s35, s29, 0x160
	s_sub_i32 s35, s3, s35
	s_lshl_b32 s58, s35, 17
	s_lshl_b32 s59, s29, 7
	s_add_u32 s58, s58, s59
	s_add_u32 s48, s42, s58
	s_addc_u32 s49, s43, 0
	ds_read2_b32 v[8:9], v4 offset0:0 offset1:33
	ds_read2_b32 v[10:11], v4 offset0:66 offset1:99
	ds_read2_b32 v[12:13], v4 offset0:132 offset1:165
	ds_read2_b32 v[14:15], v4 offset0:198 offset1:231
	s_waitcnt lgkmcnt(0)
	v_cvt_pk_bf16_f32 v48, v8, v9
	v_cvt_pk_bf16_f32 v49, v10, v11
	v_cvt_pk_bf16_f32 v50, v12, v13
	v_cvt_pk_bf16_f32 v51, v14, v15
	global_store_dwordx4 v6, v[48:51], s[48:49]
	ds_read2_b32 v[8:9], v4 offset0:8 offset1:41
	ds_read2_b32 v[10:11], v4 offset0:74 offset1:107
	ds_read2_b32 v[12:13], v4 offset0:140 offset1:173
	ds_read2_b32 v[14:15], v4 offset0:206 offset1:239
	s_waitcnt lgkmcnt(0)
	v_cvt_pk_bf16_f32 v52, v8, v9
	v_cvt_pk_bf16_f32 v53, v10, v11
	v_cvt_pk_bf16_f32 v54, v12, v13
	v_cvt_pk_bf16_f32 v55, v14, v15
	v_add_u32_e32 v7, 0x8000, v6
	global_store_dwordx4 v7, v[52:55], s[48:49]
	ds_read2_b32 v[8:9], v4 offset0:16 offset1:49
	ds_read2_b32 v[10:11], v4 offset0:82 offset1:115
	ds_read2_b32 v[12:13], v4 offset0:148 offset1:181
	ds_read2_b32 v[14:15], v4 offset0:214 offset1:247
	s_waitcnt lgkmcnt(0)
	v_cvt_pk_bf16_f32 v56, v8, v9
	v_cvt_pk_bf16_f32 v57, v10, v11
	v_cvt_pk_bf16_f32 v58, v12, v13
	v_cvt_pk_bf16_f32 v59, v14, v15
	v_add_u32_e32 v7, 0x10000, v6
	global_store_dwordx4 v7, v[56:59], s[48:49]
	ds_read2_b32 v[8:9], v4 offset0:24 offset1:57
	ds_read2_b32 v[10:11], v4 offset0:90 offset1:123
	ds_read2_b32 v[12:13], v4 offset0:156 offset1:189
	ds_read2_b32 v[14:15], v4 offset0:222 offset1:255
	s_waitcnt lgkmcnt(0)
	v_cvt_pk_bf16_f32 v60, v8, v9
	v_cvt_pk_bf16_f32 v61, v10, v11
	v_cvt_pk_bf16_f32 v62, v12, v13
	v_cvt_pk_bf16_f32 v63, v14, v15
	v_add_u32_e32 v7, 0x18000, v6
	global_store_dwordx4 v7, v[60:63], s[48:49]
	s_add_i32 s3, s0, 8192
	s_mul_i32 s29, s3, 0x1745e
	s_lshr_b32 s29, s29, 25
	s_mul_i32 s35, s29, 0x160
	s_sub_i32 s35, s3, s35
	s_mul_i32 s58, s29, 0x2c0000
	s_lshl_b32 s59, s35, 7
	s_add_u32 s58, s58, s59
	s_add_u32 s46, s10, s58
	s_addc_u32 s47, s11, 0
	global_load_dwordx4 v[48:51], v2, s[46:47] nt
	v_add_u32_e32 v7, 0x58000, v2
	global_load_dwordx4 v[52:55], v7, s[46:47] nt
	v_add_u32_e32 v7, 0xb0000, v2
	global_load_dwordx4 v[56:59], v7, s[46:47] nt
	v_add_u32_e32 v7, 0x108000, v2
	global_load_dwordx4 v[60:63], v7, s[46:47] nt
	v_add_u32_e32 v7, 0x160000, v2
	global_load_dwordx4 v[64:67], v7, s[46:47] nt
	v_add_u32_e32 v7, 0x1b8000, v2
	global_load_dwordx4 v[68:71], v7, s[46:47] nt
	v_add_u32_e32 v7, 0x210000, v2
	global_load_dwordx4 v[72:75], v7, s[46:47] nt
	v_add_u32_e32 v7, 0x268000, v2
	global_load_dwordx4 v[76:79], v7, s[46:47] nt
	s_waitcnt vmcnt(24)
	ds_write_b32 v3, v80
	ds_write_b32 v3, v81 offset:4
	ds_write_b32 v3, v82 offset:8
	ds_write_b32 v3, v83 offset:12
	ds_write_b32 v3, v84 offset:1056
	ds_write_b32 v3, v85 offset:1060
	ds_write_b32 v3, v86 offset:1064
	ds_write_b32 v3, v87 offset:1068
	ds_write_b32 v3, v88 offset:2112
	ds_write_b32 v3, v89 offset:2116
	ds_write_b32 v3, v90 offset:2120
	ds_write_b32 v3, v91 offset:2124
	ds_write_b32 v3, v92 offset:3168
	ds_write_b32 v3, v93 offset:3172
	ds_write_b32 v3, v94 offset:3176
	ds_write_b32 v3, v95 offset:3180
	ds_write_b32 v3, v96 offset:4224
	ds_write_b32 v3, v97 offset:4228
	ds_write_b32 v3, v98 offset:4232
	ds_write_b32 v3, v99 offset:4236
	ds_write_b32 v3, v100 offset:5280
	ds_write_b32 v3, v101 offset:5284
	ds_write_b32 v3, v102 offset:5288
	ds_write_b32 v3, v103 offset:5292
	ds_write_b32 v3, v104 offset:6336
	ds_write_b32 v3, v105 offset:6340
	ds_write_b32 v3, v106 offset:6344
	ds_write_b32 v3, v107 offset:6348
	ds_write_b32 v3, v108 offset:7392
	ds_write_b32 v3, v109 offset:7396
	ds_write_b32 v3, v110 offset:7400
	ds_write_b32 v3, v111 offset:7404
	s_waitcnt lgkmcnt(0)
	s_add_i32 s3, s0, 6144
	s_mul_i32 s29, s3, 0x1745e
	s_lshr_b32 s29, s29, 25
	s_mul_i32 s35, s29, 0x160
	s_sub_i32 s35, s3, s35
	s_lshl_b32 s58, s35, 17
	s_lshl_b32 s59, s29, 7
	s_add_u32 s58, s58, s59
	s_add_u32 s48, s42, s58
	s_addc_u32 s49, s43, 0
	ds_read2_b32 v[8:9], v4 offset0:0 offset1:33
	ds_read2_b32 v[10:11], v4 offset0:66 offset1:99
	ds_read2_b32 v[12:13], v4 offset0:132 offset1:165
	ds_read2_b32 v[14:15], v4 offset0:198 offset1:231
	s_waitcnt lgkmcnt(0)
	v_cvt_pk_bf16_f32 v80, v8, v9
	v_cvt_pk_bf16_f32 v81, v10, v11
	v_cvt_pk_bf16_f32 v82, v12, v13
	v_cvt_pk_bf16_f32 v83, v14, v15
	global_store_dwordx4 v6, v[80:83], s[48:49]
	ds_read2_b32 v[8:9], v4 offset0:8 offset1:41
	ds_read2_b32 v[10:11], v4 offset0:74 offset1:107
	ds_read2_b32 v[12:13], v4 offset0:140 offset1:173
	ds_read2_b32 v[14:15], v4 offset0:206 offset1:239
	s_waitcnt lgkmcnt(0)
	v_cvt_pk_bf16_f32 v84, v8, v9
	v_cvt_pk_bf16_f32 v85, v10, v11
	v_cvt_pk_bf16_f32 v86, v12, v13
	v_cvt_pk_bf16_f32 v87, v14, v15
	v_add_u32_e32 v7, 0x8000, v6
	global_store_dwordx4 v7, v[84:87], s[48:49]
	ds_read2_b32 v[8:9], v4 offset0:16 offset1:49
	ds_read2_b32 v[10:11], v4 offset0:82 offset1:115
	ds_read2_b32 v[12:13], v4 offset0:148 offset1:181
	ds_read2_b32 v[14:15], v4 offset0:214 offset1:247
	s_waitcnt lgkmcnt(0)
	v_cvt_pk_bf16_f32 v88, v8, v9
	v_cvt_pk_bf16_f32 v89, v10, v11
	v_cvt_pk_bf16_f32 v90, v12, v13
	v_cvt_pk_bf16_f32 v91, v14, v15
	v_add_u32_e32 v7, 0x10000, v6
	global_store_dwordx4 v7, v[88:91], s[48:49]
	ds_read2_b32 v[8:9], v4 offset0:24 offset1:57
	ds_read2_b32 v[10:11], v4 offset0:90 offset1:123
	ds_read2_b32 v[12:13], v4 offset0:156 offset1:189
	ds_read2_b32 v[14:15], v4 offset0:222 offset1:255
	s_waitcnt lgkmcnt(0)
	v_cvt_pk_bf16_f32 v92, v8, v9
	v_cvt_pk_bf16_f32 v93, v10, v11
	v_cvt_pk_bf16_f32 v94, v12, v13
	v_cvt_pk_bf16_f32 v95, v14, v15
	v_add_u32_e32 v7, 0x18000, v6
	global_store_dwordx4 v7, v[92:95], s[48:49]
	s_add_i32 s3, s0, 9216
	s_mul_i32 s29, s3, 0x1745e
	s_lshr_b32 s29, s29, 25
	s_mul_i32 s35, s29, 0x160
	s_sub_i32 s35, s3, s35
	s_mul_i32 s58, s29, 0x2c0000
	s_lshl_b32 s59, s35, 7
	s_add_u32 s58, s58, s59
	s_add_u32 s46, s10, s58
	s_addc_u32 s47, s11, 0
	global_load_dwordx4 v[80:83], v2, s[46:47] nt
	v_add_u32_e32 v7, 0x58000, v2
	global_load_dwordx4 v[84:87], v7, s[46:47] nt
	v_add_u32_e32 v7, 0xb0000, v2
	global_load_dwordx4 v[88:91], v7, s[46:47] nt
	v_add_u32_e32 v7, 0x108000, v2
	global_load_dwordx4 v[92:95], v7, s[46:47] nt
	v_add_u32_e32 v7, 0x160000, v2
	global_load_dwordx4 v[96:99], v7, s[46:47] nt
	v_add_u32_e32 v7, 0x1b8000, v2
	global_load_dwordx4 v[100:103], v7, s[46:47] nt
	v_add_u32_e32 v7, 0x210000, v2
	global_load_dwordx4 v[104:107], v7, s[46:47] nt
	v_add_u32_e32 v7, 0x268000, v2
	global_load_dwordx4 v[108:111], v7, s[46:47] nt
	s_waitcnt vmcnt(24)
	ds_write_b32 v3, v16
	ds_write_b32 v3, v17 offset:4
	ds_write_b32 v3, v18 offset:8
	ds_write_b32 v3, v19 offset:12
	ds_write_b32 v3, v20 offset:1056
	ds_write_b32 v3, v21 offset:1060
	ds_write_b32 v3, v22 offset:1064
	ds_write_b32 v3, v23 offset:1068
	ds_write_b32 v3, v24 offset:2112
	ds_write_b32 v3, v25 offset:2116
	ds_write_b32 v3, v26 offset:2120
	ds_write_b32 v3, v27 offset:2124
	ds_write_b32 v3, v28 offset:3168
	ds_write_b32 v3, v29 offset:3172
	ds_write_b32 v3, v30 offset:3176
	ds_write_b32 v3, v31 offset:3180
	ds_write_b32 v3, v32 offset:4224
	ds_write_b32 v3, v33 offset:4228
	ds_write_b32 v3, v34 offset:4232
	ds_write_b32 v3, v35 offset:4236
	ds_write_b32 v3, v36 offset:5280
	ds_write_b32 v3, v37 offset:5284
	ds_write_b32 v3, v38 offset:5288
	ds_write_b32 v3, v39 offset:5292
	ds_write_b32 v3, v40 offset:6336
	ds_write_b32 v3, v41 offset:6340
	ds_write_b32 v3, v42 offset:6344
	ds_write_b32 v3, v43 offset:6348
	ds_write_b32 v3, v44 offset:7392
	ds_write_b32 v3, v45 offset:7396
	ds_write_b32 v3, v46 offset:7400
	ds_write_b32 v3, v47 offset:7404
	s_waitcnt lgkmcnt(0)
	s_add_i32 s3, s0, 7168
	s_mul_i32 s29, s3, 0x1745e
	s_lshr_b32 s29, s29, 25
	s_mul_i32 s35, s29, 0x160
	s_sub_i32 s35, s3, s35
	s_lshl_b32 s58, s35, 17
	s_lshl_b32 s59, s29, 7
	s_add_u32 s58, s58, s59
	s_add_u32 s48, s42, s58
	s_addc_u32 s49, s43, 0
	ds_read2_b32 v[8:9], v4 offset0:0 offset1:33
	ds_read2_b32 v[10:11], v4 offset0:66 offset1:99
	ds_read2_b32 v[12:13], v4 offset0:132 offset1:165
	ds_read2_b32 v[14:15], v4 offset0:198 offset1:231
	s_waitcnt lgkmcnt(0)
	v_cvt_pk_bf16_f32 v16, v8, v9
	v_cvt_pk_bf16_f32 v17, v10, v11
	v_cvt_pk_bf16_f32 v18, v12, v13
	v_cvt_pk_bf16_f32 v19, v14, v15
	global_store_dwordx4 v6, v[16:19], s[48:49]
	ds_read2_b32 v[8:9], v4 offset0:8 offset1:41
	ds_read2_b32 v[10:11], v4 offset0:74 offset1:107
	ds_read2_b32 v[12:13], v4 offset0:140 offset1:173
	ds_read2_b32 v[14:15], v4 offset0:206 offset1:239
	s_waitcnt lgkmcnt(0)
	v_cvt_pk_bf16_f32 v20, v8, v9
	v_cvt_pk_bf16_f32 v21, v10, v11
	v_cvt_pk_bf16_f32 v22, v12, v13
	v_cvt_pk_bf16_f32 v23, v14, v15
	v_add_u32_e32 v7, 0x8000, v6
	global_store_dwordx4 v7, v[20:23], s[48:49]
	ds_read2_b32 v[8:9], v4 offset0:16 offset1:49
	ds_read2_b32 v[10:11], v4 offset0:82 offset1:115
	ds_read2_b32 v[12:13], v4 offset0:148 offset1:181
	ds_read2_b32 v[14:15], v4 offset0:214 offset1:247
	s_waitcnt lgkmcnt(0)
	v_cvt_pk_bf16_f32 v24, v8, v9
	v_cvt_pk_bf16_f32 v25, v10, v11
	v_cvt_pk_bf16_f32 v26, v12, v13
	v_cvt_pk_bf16_f32 v27, v14, v15
	v_add_u32_e32 v7, 0x10000, v6
	global_store_dwordx4 v7, v[24:27], s[48:49]
	ds_read2_b32 v[8:9], v4 offset0:24 offset1:57
	ds_read2_b32 v[10:11], v4 offset0:90 offset1:123
	ds_read2_b32 v[12:13], v4 offset0:156 offset1:189
	ds_read2_b32 v[14:15], v4 offset0:222 offset1:255
	s_waitcnt lgkmcnt(0)
	v_cvt_pk_bf16_f32 v28, v8, v9
	v_cvt_pk_bf16_f32 v29, v10, v11
	v_cvt_pk_bf16_f32 v30, v12, v13
	v_cvt_pk_bf16_f32 v31, v14, v15
	v_add_u32_e32 v7, 0x18000, v6
	global_store_dwordx4 v7, v[28:31], s[48:49]
	s_waitcnt vmcnt(16)
	ds_write_b32 v3, v48
	ds_write_b32 v3, v49 offset:4
	ds_write_b32 v3, v50 offset:8
	ds_write_b32 v3, v51 offset:12
	ds_write_b32 v3, v52 offset:1056
	ds_write_b32 v3, v53 offset:1060
	ds_write_b32 v3, v54 offset:1064
	ds_write_b32 v3, v55 offset:1068
	ds_write_b32 v3, v56 offset:2112
	ds_write_b32 v3, v57 offset:2116
	ds_write_b32 v3, v58 offset:2120
	ds_write_b32 v3, v59 offset:2124
	ds_write_b32 v3, v60 offset:3168
	ds_write_b32 v3, v61 offset:3172
	ds_write_b32 v3, v62 offset:3176
	ds_write_b32 v3, v63 offset:3180
	ds_write_b32 v3, v64 offset:4224
	ds_write_b32 v3, v65 offset:4228
	ds_write_b32 v3, v66 offset:4232
	ds_write_b32 v3, v67 offset:4236
	ds_write_b32 v3, v68 offset:5280
	ds_write_b32 v3, v69 offset:5284
	ds_write_b32 v3, v70 offset:5288
	ds_write_b32 v3, v71 offset:5292
	ds_write_b32 v3, v72 offset:6336
	ds_write_b32 v3, v73 offset:6340
	ds_write_b32 v3, v74 offset:6344
	ds_write_b32 v3, v75 offset:6348
	ds_write_b32 v3, v76 offset:7392
	ds_write_b32 v3, v77 offset:7396
	ds_write_b32 v3, v78 offset:7400
	ds_write_b32 v3, v79 offset:7404
	s_waitcnt lgkmcnt(0)
	s_add_i32 s3, s0, 8192
	s_mul_i32 s29, s3, 0x1745e
	s_lshr_b32 s29, s29, 25
	s_mul_i32 s35, s29, 0x160
	s_sub_i32 s35, s3, s35
	s_lshl_b32 s58, s35, 17
	s_lshl_b32 s59, s29, 7
	s_add_u32 s58, s58, s59
	s_add_u32 s48, s42, s58
	s_addc_u32 s49, s43, 0
	ds_read2_b32 v[8:9], v4 offset0:0 offset1:33
	ds_read2_b32 v[10:11], v4 offset0:66 offset1:99
	ds_read2_b32 v[12:13], v4 offset0:132 offset1:165
	ds_read2_b32 v[14:15], v4 offset0:198 offset1:231
	s_waitcnt lgkmcnt(0)
	v_cvt_pk_bf16_f32 v48, v8, v9
	v_cvt_pk_bf16_f32 v49, v10, v11
	v_cvt_pk_bf16_f32 v50, v12, v13
	v_cvt_pk_bf16_f32 v51, v14, v15
	global_store_dwordx4 v6, v[48:51], s[48:49]
	ds_read2_b32 v[8:9], v4 offset0:8 offset1:41
	ds_read2_b32 v[10:11], v4 offset0:74 offset1:107
	ds_read2_b32 v[12:13], v4 offset0:140 offset1:173
	ds_read2_b32 v[14:15], v4 offset0:206 offset1:239
	s_waitcnt lgkmcnt(0)
	v_cvt_pk_bf16_f32 v52, v8, v9
	v_cvt_pk_bf16_f32 v53, v10, v11
	v_cvt_pk_bf16_f32 v54, v12, v13
	v_cvt_pk_bf16_f32 v55, v14, v15
	v_add_u32_e32 v7, 0x8000, v6
	global_store_dwordx4 v7, v[52:55], s[48:49]
	ds_read2_b32 v[8:9], v4 offset0:16 offset1:49
	ds_read2_b32 v[10:11], v4 offset0:82 offset1:115
	ds_read2_b32 v[12:13], v4 offset0:148 offset1:181
	ds_read2_b32 v[14:15], v4 offset0:214 offset1:247
	s_waitcnt lgkmcnt(0)
	v_cvt_pk_bf16_f32 v56, v8, v9
	v_cvt_pk_bf16_f32 v57, v10, v11
	v_cvt_pk_bf16_f32 v58, v12, v13
	v_cvt_pk_bf16_f32 v59, v14, v15
	v_add_u32_e32 v7, 0x10000, v6
	global_store_dwordx4 v7, v[56:59], s[48:49]
	ds_read2_b32 v[8:9], v4 offset0:24 offset1:57
	ds_read2_b32 v[10:11], v4 offset0:90 offset1:123
	ds_read2_b32 v[12:13], v4 offset0:156 offset1:189
	ds_read2_b32 v[14:15], v4 offset0:222 offset1:255
	s_waitcnt lgkmcnt(0)
	v_cvt_pk_bf16_f32 v60, v8, v9
	v_cvt_pk_bf16_f32 v61, v10, v11
	v_cvt_pk_bf16_f32 v62, v12, v13
	v_cvt_pk_bf16_f32 v63, v14, v15
	v_add_u32_e32 v7, 0x18000, v6
	global_store_dwordx4 v7, v[60:63], s[48:49]
	s_waitcnt vmcnt(8)
	ds_write_b32 v3, v80
	ds_write_b32 v3, v81 offset:4
	ds_write_b32 v3, v82 offset:8
	ds_write_b32 v3, v83 offset:12
	ds_write_b32 v3, v84 offset:1056
	ds_write_b32 v3, v85 offset:1060
	ds_write_b32 v3, v86 offset:1064
	ds_write_b32 v3, v87 offset:1068
	ds_write_b32 v3, v88 offset:2112
	ds_write_b32 v3, v89 offset:2116
	ds_write_b32 v3, v90 offset:2120
	ds_write_b32 v3, v91 offset:2124
	ds_write_b32 v3, v92 offset:3168
	ds_write_b32 v3, v93 offset:3172
	ds_write_b32 v3, v94 offset:3176
	ds_write_b32 v3, v95 offset:3180
	ds_write_b32 v3, v96 offset:4224
	ds_write_b32 v3, v97 offset:4228
	ds_write_b32 v3, v98 offset:4232
	ds_write_b32 v3, v99 offset:4236
	ds_write_b32 v3, v100 offset:5280
	ds_write_b32 v3, v101 offset:5284
	ds_write_b32 v3, v102 offset:5288
	ds_write_b32 v3, v103 offset:5292
	ds_write_b32 v3, v104 offset:6336
	ds_write_b32 v3, v105 offset:6340
	ds_write_b32 v3, v106 offset:6344
	ds_write_b32 v3, v107 offset:6348
	ds_write_b32 v3, v108 offset:7392
	ds_write_b32 v3, v109 offset:7396
	ds_write_b32 v3, v110 offset:7400
	ds_write_b32 v3, v111 offset:7404
	s_waitcnt lgkmcnt(0)
	s_add_i32 s3, s0, 9216
	s_mul_i32 s29, s3, 0x1745e
	s_lshr_b32 s29, s29, 25
	s_mul_i32 s35, s29, 0x160
	s_sub_i32 s35, s3, s35
	s_lshl_b32 s58, s35, 17
	s_lshl_b32 s59, s29, 7
	s_add_u32 s58, s58, s59
	s_add_u32 s48, s42, s58
	s_addc_u32 s49, s43, 0
	ds_read2_b32 v[8:9], v4 offset0:0 offset1:33
	ds_read2_b32 v[10:11], v4 offset0:66 offset1:99
	ds_read2_b32 v[12:13], v4 offset0:132 offset1:165
	ds_read2_b32 v[14:15], v4 offset0:198 offset1:231
	s_waitcnt lgkmcnt(0)
	v_cvt_pk_bf16_f32 v80, v8, v9
	v_cvt_pk_bf16_f32 v81, v10, v11
	v_cvt_pk_bf16_f32 v82, v12, v13
	v_cvt_pk_bf16_f32 v83, v14, v15
	global_store_dwordx4 v6, v[80:83], s[48:49]
	ds_read2_b32 v[8:9], v4 offset0:8 offset1:41
	ds_read2_b32 v[10:11], v4 offset0:74 offset1:107
	ds_read2_b32 v[12:13], v4 offset0:140 offset1:173
	ds_read2_b32 v[14:15], v4 offset0:206 offset1:239
	s_waitcnt lgkmcnt(0)
	v_cvt_pk_bf16_f32 v84, v8, v9
	v_cvt_pk_bf16_f32 v85, v10, v11
	v_cvt_pk_bf16_f32 v86, v12, v13
	v_cvt_pk_bf16_f32 v87, v14, v15
	v_add_u32_e32 v7, 0x8000, v6
	global_store_dwordx4 v7, v[84:87], s[48:49]
	ds_read2_b32 v[8:9], v4 offset0:16 offset1:49
	ds_read2_b32 v[10:11], v4 offset0:82 offset1:115
	ds_read2_b32 v[12:13], v4 offset0:148 offset1:181
	ds_read2_b32 v[14:15], v4 offset0:214 offset1:247
	s_waitcnt lgkmcnt(0)
	v_cvt_pk_bf16_f32 v88, v8, v9
	v_cvt_pk_bf16_f32 v89, v10, v11
	v_cvt_pk_bf16_f32 v90, v12, v13
	v_cvt_pk_bf16_f32 v91, v14, v15
	v_add_u32_e32 v7, 0x10000, v6
	global_store_dwordx4 v7, v[88:91], s[48:49]
	ds_read2_b32 v[8:9], v4 offset0:24 offset1:57
	ds_read2_b32 v[10:11], v4 offset0:90 offset1:123
	ds_read2_b32 v[12:13], v4 offset0:156 offset1:189
	ds_read2_b32 v[14:15], v4 offset0:222 offset1:255
	s_waitcnt lgkmcnt(0)
	v_cvt_pk_bf16_f32 v92, v8, v9
	v_cvt_pk_bf16_f32 v93, v10, v11
	v_cvt_pk_bf16_f32 v94, v12, v13
	v_cvt_pk_bf16_f32 v95, v14, v15
	v_add_u32_e32 v7, 0x18000, v6
	global_store_dwordx4 v7, v[92:95], s[48:49]
	s_branch .LBB0_376
.Lconv_classA:
	v_readlane_b32 s0, v254, 2
	s_lshl_b32 s0, s0, 3
	s_add_i32 s0, s0, s78
	v_readlane_b32 s70, v254, 0
	v_readlane_b32 s71, v254, 1
	s_sub_u32 s70, s70, 0xc8
	s_subb_u32 s71, s71, 0
	s_load_dwordx4 s[4:7], s[70:71], 0x68
	s_load_dwordx2 s[8:9], s[70:71], 0x78
	s_load_dwordx2 s[10:11], s[70:71], 0x90
	s_add_u32 s12, s26, 0x2600000
	s_addc_u32 s13, s27, 0
	s_add_u32 s30, s26, 0x3200000
	s_addc_u32 s31, s27, 0
	s_add_u32 s42, s26, 0x3a00000
	s_addc_u32 s43, s27, 0
	v_and_b32_e32 v7, 63, v0
	v_lshrrev_b32_e32 v8, 3, v7
	v_and_b32_e32 v9, 7, v7
	v_lshlrev_b32_e32 v1, 13, v8
	v_lshl_add_u32 v1, v9, 4, v1
	v_mul_u32_u24_e32 v2, 0xb000, v8
	v_lshl_add_u32 v2, v9, 4, v2
	s_lshl_b32 s1, s78, 14
	v_mul_u32_u24_e32 v3, 33, v8
	v_lshl_add_u32 v3, v9, 2, v3
	v_lshl_add_u32 v3, v3, 2, s1
	v_mul_u32_u24_e32 v4, 0x108, v9
	v_add_u32_e32 v4, v4, v8
	v_lshl_add_u32 v4, v4, 2, s1
	v_mul_u32_u24_e32 v5, 0x1800, v8
	v_lshl_add_u32 v5, v9, 4, v5
	v_lshlrev_b32_e32 v6, 12, v8
	v_lshl_add_u32 v6, v9, 4, v6
	s_waitcnt lgkmcnt(0)
	s_add_i32 s3, s0, 10240
	s_mul_i32 s29, s3, 0x1745e
	s_lshr_b32 s29, s29, 25
	s_mul_i32 s35, s29, 0x160
	s_sub_i32 s35, s3, s35
	s_mul_i32 s58, s29, 0x2c0000
	s_lshl_b32 s59, s35, 7
	s_add_u32 s58, s58, s59
	s_add_u32 s46, s10, s58
	s_addc_u32 s47, s11, 0
	global_load_dwordx4 v[16:19], v2, s[46:47] nt
	v_add_u32_e32 v7, 0x58000, v2
	global_load_dwordx4 v[20:23], v7, s[46:47] nt
	v_add_u32_e32 v7, 0xb0000, v2
	global_load_dwordx4 v[24:27], v7, s[46:47] nt
	v_add_u32_e32 v7, 0x108000, v2
	global_load_dwordx4 v[28:31], v7, s[46:47] nt
	v_add_u32_e32 v7, 0x160000, v2
	global_load_dwordx4 v[32:35], v7, s[46:47] nt
	v_add_u32_e32 v7, 0x1b8000, v2
	global_load_dwordx4 v[36:39], v7, s[46:47] nt
	v_add_u32_e32 v7, 0x210000, v2
	global_load_dwordx4 v[40:43], v7, s[46:47] nt
	v_add_u32_e32 v7, 0x268000, v2
	global_load_dwordx4 v[44:47], v7, s[46:47] nt
	s_waitcnt vmcnt(0)
	ds_write_b32 v3, v16
	ds_write_b32 v3, v17 offset:4
	ds_write_b32 v3, v18 offset:8
	ds_write_b32 v3, v19 offset:12
	ds_write_b32 v3, v20 offset:1056
	ds_write_b32 v3, v21 offset:1060
	ds_write_b32 v3, v22 offset:1064
	ds_write_b32 v3, v23 offset:1068
	ds_write_b32 v3, v24 offset:2112
	ds_write_b32 v3, v25 offset:2116
	ds_write_b32 v3, v26 offset:2120
	ds_write_b32 v3, v27 offset:2124
	ds_write_b32 v3, v28 offset:3168
	ds_write_b32 v3, v29 offset:3172
	ds_write_b32 v3, v30 offset:3176
	ds_write_b32 v3, v31 offset:3180
	ds_write_b32 v3, v32 offset:4224
	ds_write_b32 v3, v33 offset:4228
	ds_write_b32 v3, v34 offset:4232
	ds_write_b32 v3, v35 offset:4236
	ds_write_b32 v3, v36 offset:5280
	ds_write_b32 v3, v37 offset:5284
	ds_write_b32 v3, v38 offset:5288
	ds_write_b32 v3, v39 offset:5292
	ds_write_b32 v3, v40 offset:6336
	ds_write_b32 v3, v41 offset:6340
	ds_write_b32 v3, v42 offset:6344
	ds_write_b32 v3, v43 offset:6348
	ds_write_b32 v3, v44 offset:7392
	ds_write_b32 v3, v45 offset:7396
	ds_write_b32 v3, v46 offset:7400
	ds_write_b32 v3, v47 offset:7404
	s_waitcnt lgkmcnt(0)
	s_add_i32 s3, s0, 10240
	s_mul_i32 s29, s3, 0x1745e
	s_lshr_b32 s29, s29, 25
	s_mul_i32 s35, s29, 0x160
	s_sub_i32 s35, s3, s35
	s_lshl_b32 s58, s35, 17
	s_lshl_b32 s59, s29, 7
	s_add_u32 s58, s58, s59
	s_add_u32 s48, s42, s58
	s_addc_u32 s49, s43, 0
	ds_read2_b32 v[8:9], v4 offset0:0 offset1:33
	ds_read2_b32 v[10:11], v4 offset0:66 offset1:99
	ds_read2_b32 v[12:13], v4 offset0:132 offset1:165
	ds_read2_b32 v[14:15], v4 offset0:198 offset1:231
	s_waitcnt lgkmcnt(0)
	v_cvt_pk_bf16_f32 v16, v8, v9
	v_cvt_pk_bf16_f32 v17, v10, v11
	v_cvt_pk_bf16_f32 v18, v12, v13
	v_cvt_pk_bf16_f32 v19, v14, v15
	global_store_dwordx4 v6, v[16:19], s[48:49]
	ds_read2_b32 v[8:9], v4 offset0:8 offset1:41
	ds_read2_b32 v[10:11], v4 offset0:74 offset1:107
	ds_read2_b32 v[12:13], v4 offset0:140 offset1:173
	ds_read2_b32 v[14:15], v4 offset0:206 offset1:239
	s_waitcnt lgkmcnt(0)
	v_cvt_pk_bf16_f32 v20, v8, v9
	v_cvt_pk_bf16_f32 v21, v10, v11
	v_cvt_pk_bf16_f32 v22, v12, v13
	v_cvt_pk_bf16_f32 v23, v14, v15
	v_add_u32_e32 v7, 0x8000, v6
	global_store_dwordx4 v7, v[20:23], s[48:49]
	ds_read2_b32 v[8:9], v4 offset0:16 offset1:49
	ds_read2_b32 v[10:11], v4 offset0:82 offset1:115
	ds_read2_b32 v[12:13], v4 offset0:148 offset1:181
	ds_read2_b32 v[14:15], v4 offset0:214 offset1:247
	s_waitcnt lgkmcnt(0)
	v_cvt_pk_bf16_f32 v24, v8, v9
	v_cvt_pk_bf16_f32 v25, v10, v11
	v_cvt_pk_bf16_f32 v26, v12, v13
	v_cvt_pk_bf16_f32 v27, v14, v15
	v_add_u32_e32 v7, 0x10000, v6
	global_store_dwordx4 v7, v[24:27], s[48:49]
	ds_read2_b32 v[8:9], v4 offset0:24 offset1:57
	ds_read2_b32 v[10:11], v4 offset0:90 offset1:123
	ds_read2_b32 v[12:13], v4 offset0:156 offset1:189
	ds_read2_b32 v[14:15], v4 offset0:222 offset1:255
	s_waitcnt lgkmcnt(0)
	v_cvt_pk_bf16_f32 v28, v8, v9
	v_cvt_pk_bf16_f32 v29, v10, v11
	v_cvt_pk_bf16_f32 v30, v12, v13
	v_cvt_pk_bf16_f32 v31, v14, v15
	v_add_u32_e32 v7, 0x18000, v6
	global_store_dwordx4 v7, v[28:31], s[48:49]
	s_branch .LBB0_376
